# flash loops: LDS-DMA issue block without the VGPR temp (readfirstlane of the offset + s_add into m0), 4 fewer instructions per block
# speedup vs baseline: 1.0008x; 1.0008x over previous
; #define MFMA(a, b, c) __builtin_amdgcn_mfma_f32_32x32x16_bf16((a), (b), (c), 0, 0, 0)
;     ...
;   float mc = m * c2;
;   if (MODE == 2) mc = selbit ? mc : 1e30f;
;   const f32x2v c2v = {c2, c2}, mcv = {-mc, -mc};
;   f32x2v rs2 = {0.f, 0.f};
; #pragma unroll
;   for (int ks = 0; ks < 2; ++ks)
; #pragma unroll
;     for (int st = 0; st < 2; ++st) {
;       union { unsigned u[4]; bf16x8 v; } pf;
; #pragma unroll
;       for (int j = 0; j < 4; ++j) {
;         const int i0 = 8 * st + 2 * j;
;         f32x2v t = {S[ks][i0], S[ks][i0 + 1]};
;         t = __builtin_elementwise_fma(t, c2v, mcv);
;         f32x2v pv;
;         if (variant == 1) { pv = t; } else {
;         pv.x = __builtin_amdgcn_exp2f(t.x);
;         pv.y = __builtin_amdgcn_exp2f(t.y);
;         }
;         if (MODE != 0) {
;           if (need_mask) {
;             pv.x = (S[ks][i0] > -1e29f) ? pv.x : 0.f;
;             pv.y = (S[ks][i0 + 1] > -1e29f) ? pv.y : 0.f;
;           }
;         }
;         rs2 += pv;
;         pf.u[j] = __builtin_bit_cast(unsigned, __builtin_convertvector(pv, hwbf16x2));
;       }
; #pragma unroll
;       for (int d = 0; d < DV / 32; ++d) {
;         const char* vp = base + C::KBYTES + (d * 32 + lr) * C::VSTR + (ks * 32 + 16 * st + 4 * lh) * 2;
;         const s16x4 lo = *(const s16x4*)vp, hi = *(const s16x4*)(vp + 16);
;         const bf16x8 vf = __builtin_shufflevector(lo, hi, 0, 1, 2, 3, 4, 5, 6, 7);
;         O[d] = MFMA(vf, pf.v, O[d]);
;       }
;     }
.LBB0_362:
	s_cmp_eq_u64 s[8:9], 0
	s_cbranch_scc1 .Lfast_mla1
	v_mul_f32_e32 v104, 0xbe16c740, v104
	s_mov_b32 s12, 0x3e16c740
	v_pk_fma_f32 v[118:119], v[50:51], s[12:13], v[104:105] op_sel_hi:[1,0,0]
	v_cmp_lt_f32_e32 vcc, s33, v50
	v_exp_f32_e32 v118, v118
	v_exp_f32_e32 v119, v119
	v_cndmask_b32_e32 v50, 0, v118, vcc
	v_cmp_lt_f32_e32 vcc, s33, v51
	v_cndmask_b32_e64 v126, v118, v50, s[8:9]
	s_nop 0
	v_cndmask_b32_e32 v51, 0, v119, vcc
	v_cndmask_b32_e64 v127, v119, v51, s[8:9]
	v_pk_fma_f32 v[50:51], v[52:53], s[12:13], v[104:105] op_sel_hi:[1,0,0]
	v_cmp_lt_f32_e32 vcc, s33, v52
	v_exp_f32_e32 v50, v50
	v_exp_f32_e32 v51, v51
	v_cvt_pk_bf16_f32 v118, v126, v127
	v_cndmask_b32_e32 v52, 0, v50, vcc
	v_cmp_lt_f32_e32 vcc, s33, v53
	v_cndmask_b32_e64 v128, v50, v52, s[8:9]
	s_nop 0
	v_cndmask_b32_e32 v53, 0, v51, vcc
	v_cndmask_b32_e64 v129, v51, v53, s[8:9]
	v_pk_fma_f32 v[50:51], v[54:55], s[12:13], v[104:105] op_sel_hi:[1,0,0]
	v_cmp_lt_f32_e32 vcc, s33, v54
	v_exp_f32_e32 v50, v50
	v_exp_f32_e32 v51, v51
	v_cvt_pk_bf16_f32 v119, v128, v129
	v_cndmask_b32_e32 v52, 0, v50, vcc
	v_cmp_lt_f32_e32 vcc, s33, v55
	v_cndmask_b32_e64 v130, v50, v52, s[8:9]
	s_nop 0
	v_cndmask_b32_e32 v53, 0, v51, vcc
	v_cndmask_b32_e64 v131, v51, v53, s[8:9]
	v_pk_fma_f32 v[50:51], v[56:57], s[12:13], v[104:105] op_sel_hi:[1,0,0]
	v_cmp_lt_f32_e32 vcc, s33, v56
	v_exp_f32_e32 v50, v50
	v_exp_f32_e32 v51, v51
	v_cvt_pk_bf16_f32 v120, v130, v131
	v_cndmask_b32_e32 v52, 0, v50, vcc
	v_cmp_lt_f32_e32 vcc, s33, v57
	v_cndmask_b32_e64 v56, v50, v52, s[8:9]
	s_nop 0
	v_cndmask_b32_e32 v53, 0, v51, vcc
	v_cndmask_b32_e64 v57, v51, v53, s[8:9]
	v_cvt_pk_bf16_f32 v121, v56, v57
	v_cmp_lt_f32_e32 vcc, s33, v58
	s_waitcnt lgkmcnt(0)
	v_mfma_f32_32x32x16_bf16 v[18:33], v[216:219], v[118:121], v[18:33]
	s_waitcnt lgkmcnt(0)
	v_mfma_f32_32x32x16_bf16 v[2:17], v[220:223], v[118:121], v[2:17]
	v_add_f32_e64 v52, v126, 0
	v_add_f32_e64 v53, v127, 0
	v_add_f32_e64 v52, v128, v52
	v_add_f32_e64 v53, v129, v53
	v_add_f32_e64 v52, v130, v52
	v_add_f32_e64 v53, v131, v53
	v_pk_add_f32 v[118:119], v[56:57], v[52:53]
	v_pk_fma_f32 v[52:53], v[58:59], s[12:13], v[104:105] op_sel_hi:[1,0,0]
	s_nop 0
	v_exp_f32_e32 v52, v52
	v_exp_f32_e32 v53, v53
	v_cndmask_b32_e32 v54, 0, v52, vcc
	v_cmp_lt_f32_e32 vcc, s33, v59
	v_cndmask_b32_e64 v120, v52, v54, s[8:9]
	s_nop 0
	v_cndmask_b32_e32 v55, 0, v53, vcc
	v_cndmask_b32_e64 v121, v53, v55, s[8:9]
	v_pk_fma_f32 v[54:55], v[60:61], s[12:13], v[104:105] op_sel_hi:[1,0,0]
	v_cmp_lt_f32_e32 vcc, s33, v60
	v_exp_f32_e32 v53, v54
	v_exp_f32_e32 v54, v55
	v_cvt_pk_bf16_f32 v52, v120, v121
	v_cndmask_b32_e32 v55, 0, v53, vcc
	v_cmp_lt_f32_e32 vcc, s33, v61
	v_cndmask_b32_e64 v60, v53, v55, s[8:9]
	s_nop 0
	v_cndmask_b32_e32 v56, 0, v54, vcc
	v_cndmask_b32_e64 v61, v54, v56, s[8:9]
	v_pk_fma_f32 v[54:55], v[62:63], s[12:13], v[104:105] op_sel_hi:[1,0,0]
	v_cmp_lt_f32_e32 vcc, s33, v62
	v_exp_f32_e32 v54, v54
	v_exp_f32_e32 v55, v55
	v_cvt_pk_bf16_f32 v53, v60, v61
	v_cndmask_b32_e32 v56, 0, v54, vcc
	v_cmp_lt_f32_e32 vcc, s33, v63
	v_cndmask_b32_e64 v62, v54, v56, s[8:9]
	s_nop 0
	v_cndmask_b32_e32 v57, 0, v55, vcc
	v_cndmask_b32_e64 v63, v55, v57, s[8:9]
	v_pk_fma_f32 v[56:57], v[64:65], s[12:13], v[104:105] op_sel_hi:[1,0,0]
	v_cmp_lt_f32_e32 vcc, s33, v64
	v_exp_f32_e32 v55, v56
	v_exp_f32_e32 v56, v57
	v_cvt_pk_bf16_f32 v54, v62, v63
	v_cndmask_b32_e32 v57, 0, v55, vcc
	v_cmp_lt_f32_e32 vcc, s33, v65
	v_cndmask_b32_e64 v64, v55, v57, s[8:9]
	s_nop 0
	v_cndmask_b32_e32 v58, 0, v56, vcc
	v_cndmask_b32_e64 v65, v56, v58, s[8:9]
	v_cvt_pk_bf16_f32 v55, v64, v65
	v_cmp_lt_f32_e32 vcc, s33, v34
	s_nop 0
	v_mfma_f32_32x32x16_bf16 v[18:33], v[224:227], v[52:55], v[18:33]
	s_waitcnt lgkmcnt(0)
; #define MFMA(a, b, c) __builtin_amdgcn_mfma_f32_32x32x16_bf16((a), (b), (c), 0, 0, 0)
; template <int N> DI void wait_vmcnt() { asm volatile("s_waitcnt vmcnt(%0)" ::"n"(N) : "memory"); }
;     ...
; #pragma unroll
;       for (int j = 0; j < 4; ++j) {
;         const int i0 = 8 * st + 2 * j;
;         f32x2v t = {S[ks][i0], S[ks][i0 + 1]};
;         t = __builtin_elementwise_fma(t, c2v, mcv);
;         f32x2v pv;
;         if (variant == 1) { pv = t; } else {
;         pv.x = __builtin_amdgcn_exp2f(t.x);
;         pv.y = __builtin_amdgcn_exp2f(t.y);
;         }
;         if (MODE != 0) {
;           if (need_mask) {
;             pv.x = (S[ks][i0] > -1e29f) ? pv.x : 0.f;
;             pv.y = (S[ks][i0 + 1] > -1e29f) ? pv.y : 0.f;
;           }
;         }
;         rs2 += pv;
;         pf.u[j] = __builtin_bit_cast(unsigned, __builtin_convertvector(pv, hwbf16x2));
;       }
; #pragma unroll
;       for (int d = 0; d < DV / 32; ++d) {
;         const char* vp = base + C::KBYTES + (d * 32 + lr) * C::VSTR + (ks * 32 + 16 * st + 4 * lh) * 2;
;         const s16x4 lo = *(const s16x4*)vp, hi = *(const s16x4*)(vp + 16);
;         const bf16x8 vf = __builtin_shufflevector(lo, hi, 0, 1, 2, 3, 4, 5, 6, 7);
;         O[d] = MFMA(vf, pf.v, O[d]);
;       }
;     }
;   float rs = rs2.x + rs2.y;
;   rs += __shfl_xor(rs, 32);
;     ...
;   asm volatile("s_waitcnt vmcnt(0)" ::: "memory");
; #pragma unroll
;   for (int t = 0; t < NST - 1; ++t)
;     if (t < ntile) FA_ISSUE(t, t)
;   int stage = 0;
;   for (int t = 0; t < ntile; ++t) {
;     int ahead = ((ntile < t + NST - 1) ? ntile : t + NST - 1) - (t + 1);
;     if (NST == 4 && ahead >= 2) wait_vmcnt<2 * NI>();
;     else if (ahead >= 1) wait_vmcnt<NI>();
;     else wait_vmcnt<0>();
;     raw_barrier();
;     if (t + NST - 1 < ntile) {
;       const int sn = (stage == 0) ? NST - 1 : stage - 1;
;       FA_ISSUE(t + NST - 1, sn)
	v_mfma_f32_32x32x16_bf16 v[2:17], v[228:231], v[52:55], v[2:17]
	v_fma_f32 v54, v34, s12, v104
	v_fma_f32 v55, v35, s12, v104
	v_fma_f32 v56, v36, s12, v104
	v_fma_f32 v57, v37, s12, v104
	v_exp_f32_e32 v54, v54
	v_exp_f32_e32 v55, v55
	v_pk_add_f32 v[52:53], v[120:121], v[118:119]
	v_cndmask_b32_e32 v34, 0, v54, vcc
	v_cmp_lt_f32_e32 vcc, s33, v35
	v_pk_add_f32 v[52:53], v[60:61], v[52:53]
	v_cndmask_b32_e64 v54, v54, v34, s[8:9]
	v_cndmask_b32_e32 v35, 0, v55, vcc
	v_cndmask_b32_e64 v55, v55, v35, s[8:9]
	v_exp_f32_e32 v35, v56
	v_exp_f32_e32 v56, v57
	v_cmp_lt_f32_e32 vcc, s33, v36
	v_cvt_pk_bf16_f32 v34, v54, v55
	v_pk_add_f32 v[52:53], v[62:63], v[52:53]
	v_cndmask_b32_e32 v36, 0, v35, vcc
	v_cmp_lt_f32_e32 vcc, s33, v37
	v_pk_add_f32 v[52:53], v[64:65], v[52:53]
	s_nop 0
	v_cndmask_b32_e32 v37, 0, v56, vcc
	v_cndmask_b32_e64 v57, v56, v37, s[8:9]
	v_cndmask_b32_e64 v56, v35, v36, s[8:9]
	v_pk_fma_f32 v[36:37], v[38:39], s[12:13], v[104:105] op_sel_hi:[1,0,0]
	v_cmp_lt_f32_e32 vcc, s33, v38
	v_exp_f32_e32 v36, v36
	v_exp_f32_e32 v37, v37
	v_cvt_pk_bf16_f32 v35, v56, v57
	v_cndmask_b32_e32 v38, 0, v36, vcc
	v_cmp_lt_f32_e32 vcc, s33, v39
	v_cndmask_b32_e64 v58, v36, v38, s[8:9]
	s_nop 0
	v_cndmask_b32_e32 v39, 0, v37, vcc
	v_cndmask_b32_e64 v59, v37, v39, s[8:9]
	v_pk_fma_f32 v[38:39], v[40:41], s[12:13], v[104:105] op_sel_hi:[1,0,0]
	v_cmp_lt_f32_e32 vcc, s33, v40
	v_exp_f32_e32 v37, v38
	v_exp_f32_e32 v38, v39
	v_cvt_pk_bf16_f32 v36, v58, v59
	v_cndmask_b32_e32 v39, 0, v37, vcc
	v_cmp_lt_f32_e32 vcc, s33, v41
	v_cndmask_b32_e64 v60, v37, v39, s[8:9]
	s_nop 0
	v_cndmask_b32_e32 v40, 0, v38, vcc
	v_cndmask_b32_e64 v61, v38, v40, s[8:9]
	v_cvt_pk_bf16_f32 v37, v60, v61
	v_cmp_lt_f32_e32 vcc, s33, v42
	s_waitcnt lgkmcnt(0)
	v_mfma_f32_32x32x16_bf16 v[18:33], v[232:235], v[34:37], v[18:33]
	s_waitcnt lgkmcnt(0)
	v_mfma_f32_32x32x16_bf16 v[2:17], v[236:239], v[34:37], v[2:17]
	v_add_f32_e64 v34, v54, v52
	v_add_f32_e64 v35, v55, v53
	v_add_f32_e64 v34, v56, v34
	v_add_f32_e64 v35, v57, v35
	v_add_f32_e64 v34, v58, v34
	v_add_f32_e64 v35, v59, v35
	v_pk_add_f32 v[52:53], v[60:61], v[34:35]
	v_pk_fma_f32 v[34:35], v[42:43], s[12:13], v[104:105] op_sel_hi:[1,0,0]
	s_nop 0
	v_exp_f32_e32 v34, v34
	v_exp_f32_e32 v35, v35
	v_cndmask_b32_e32 v36, 0, v34, vcc
	v_cmp_lt_f32_e32 vcc, s33, v43
	v_cndmask_b32_e64 v42, v34, v36, s[8:9]
	s_nop 0
	v_cndmask_b32_e32 v37, 0, v35, vcc
	v_cndmask_b32_e64 v43, v35, v37, s[8:9]
	v_pk_fma_f32 v[36:37], v[44:45], s[12:13], v[104:105] op_sel_hi:[1,0,0]
	v_cmp_lt_f32_e32 vcc, s33, v44
	v_exp_f32_e32 v35, v36
	v_exp_f32_e32 v36, v37
	v_cvt_pk_bf16_f32 v34, v42, v43
	v_cndmask_b32_e32 v37, 0, v35, vcc
	v_cmp_lt_f32_e32 vcc, s33, v45
	v_cndmask_b32_e64 v44, v35, v37, s[8:9]
	s_nop 0
	v_cndmask_b32_e32 v38, 0, v36, vcc
	v_cndmask_b32_e64 v45, v36, v38, s[8:9]
	v_pk_fma_f32 v[36:37], v[46:47], s[12:13], v[104:105] op_sel_hi:[1,0,0]
	v_cmp_lt_f32_e32 vcc, s33, v46
	v_exp_f32_e32 v36, v36
	v_exp_f32_e32 v37, v37
	v_cvt_pk_bf16_f32 v35, v44, v45
	v_cndmask_b32_e32 v38, 0, v36, vcc
	v_cmp_lt_f32_e32 vcc, s33, v47
	v_cndmask_b32_e64 v46, v36, v38, s[8:9]
	s_nop 0
	v_cndmask_b32_e32 v39, 0, v37, vcc
	v_cndmask_b32_e64 v47, v37, v39, s[8:9]
	v_pk_fma_f32 v[38:39], v[48:49], s[12:13], v[104:105] op_sel_hi:[1,0,0]
	v_cmp_lt_f32_e32 vcc, s33, v48
	v_exp_f32_e32 v37, v38
	v_exp_f32_e32 v38, v39
	v_cvt_pk_bf16_f32 v36, v46, v47
	v_cndmask_b32_e32 v39, 0, v37, vcc
	v_cmp_lt_f32_e32 vcc, s33, v49
	v_cndmask_b32_e64 v48, v37, v39, s[8:9]
	s_nop 0
	v_cndmask_b32_e32 v40, 0, v38, vcc
	v_cndmask_b32_e64 v49, v38, v40, s[8:9]
	v_cvt_pk_bf16_f32 v37, v48, v49
	s_waitcnt lgkmcnt(0)
	s_nop 0
	v_mfma_f32_32x32x16_bf16 v[18:33], v[240:243], v[34:37], v[18:33]
	s_waitcnt lgkmcnt(0)
	v_mfma_f32_32x32x16_bf16 v[2:17], v[244:247], v[34:37], v[2:17]
	v_add_f32_e64 v34, v42, v52
	v_add_f32_e64 v35, v43, v53
	v_add_f32_e64 v34, v44, v34
	v_add_f32_e64 v35, v45, v35
	v_add_f32_e64 v34, v46, v34
	v_add_f32_e64 v35, v47, v35
	v_pk_add_f32 v[34:35], v[48:49], v[34:35]
	s_nop 0
	v_add_f32_e32 v34, v34, v35
	ds_bpermute_b32 v35, v117, v34
	s_cmp_ge_u32 s16, s19
	s_cbranch_scc1 .Ldma_m_mla1
	s_add_i32 s98, s6, 0xffffa800
	s_cmp_lg_u32 s22, 0
	s_cselect_b32 s98, s98, 0x10800
	v_readfirstlane_b32 s99, v107
	s_add_i32 m0, s99, s98
	v_readfirstlane_b32 s99, v93
	global_load_lds_dwordx4 v[102:103], off
	s_add_i32 m0, s99, s98
	v_readfirstlane_b32 s99, v108
	global_load_lds_dwordx4 v[100:101], off
	s_add_i32 m0, s99, s98
	s_nop 0
	global_load_lds_dwordx4 v[98:99], off

; #define MFMA(a, b, c) __builtin_amdgcn_mfma_f32_32x32x16_bf16((a), (b), (c), 0, 0, 0)
; template <int N> DI void wait_vmcnt() { asm volatile("s_waitcnt vmcnt(%0)" ::"n"(N) : "memory"); }
;     ...
;   float mc = m * c2;
;   if (MODE == 2) mc = selbit ? mc : 1e30f;
;   const f32x2v c2v = {c2, c2}, mcv = {-mc, -mc};
;   f32x2v rs2 = {0.f, 0.f};
; #pragma unroll
;   for (int ks = 0; ks < 2; ++ks)
; #pragma unroll
;     for (int st = 0; st < 2; ++st) {
;       union { unsigned u[4]; bf16x8 v; } pf;
; #pragma unroll
;       for (int j = 0; j < 4; ++j) {
;         const int i0 = 8 * st + 2 * j;
;         f32x2v t = {S[ks][i0], S[ks][i0 + 1]};
;         t = __builtin_elementwise_fma(t, c2v, mcv);
;         f32x2v pv;
;         if (variant == 1) { pv = t; } else {
;         pv.x = __builtin_amdgcn_exp2f(t.x);
;         pv.y = __builtin_amdgcn_exp2f(t.y);
;         }
;         if (MODE != 0) {
;           if (need_mask) {
;             pv.x = (S[ks][i0] > -1e29f) ? pv.x : 0.f;
;             pv.y = (S[ks][i0 + 1] > -1e29f) ? pv.y : 0.f;
;           }
;         }
;         rs2 += pv;
;         pf.u[j] = __builtin_bit_cast(unsigned, __builtin_convertvector(pv, hwbf16x2));
;       }
; #pragma unroll
;       for (int d = 0; d < DV / 32; ++d) {
;         const char* vp = base + C::KBYTES + (d * 32 + lr) * C::VSTR + (ks * 32 + 16 * st + 4 * lh) * 2;
;         const s16x4 lo = *(const s16x4*)vp, hi = *(const s16x4*)(vp + 16);
;         const bf16x8 vf = __builtin_shufflevector(lo, hi, 0, 1, 2, 3, 4, 5, 6, 7);
;         O[d] = MFMA(vf, pf.v, O[d]);
;       }
;     }
;   float rs = rs2.x + rs2.y;
;   rs += __shfl_xor(rs, 32);
;     ...
;   asm volatile("s_waitcnt vmcnt(0)" ::: "memory");
; #pragma unroll
;   for (int t = 0; t < NST - 1; ++t)
;     if (t < ntile) FA_ISSUE(t, t)
;   int stage = 0;
;   for (int t = 0; t < ntile; ++t) {
;     int ahead = ((ntile < t + NST - 1) ? ntile : t + NST - 1) - (t + 1);
;     if (NST == 4 && ahead >= 2) wait_vmcnt<2 * NI>();
;     else if (ahead >= 1) wait_vmcnt<NI>();
;     else wait_vmcnt<0>();
;     raw_barrier();
;     if (t + NST - 1 < ntile) {
;       const int sn = (stage == 0) ? NST - 1 : stage - 1;
;       FA_ISSUE(t + NST - 1, sn)
.Lfast_mla1:
	v_mul_f32_e32 v104, 0xbe16c740, v104
	s_mov_b32 s12, 0x3e16c740
	v_pk_fma_f32 v[118:119], v[50:51], s[12:13], v[104:105] op_sel_hi:[1,0,0]
	v_exp_f32_e32 v126, v118
	v_exp_f32_e32 v127, v119
	v_pk_fma_f32 v[50:51], v[52:53], s[12:13], v[104:105] op_sel_hi:[1,0,0]
	v_exp_f32_e32 v128, v50
	v_exp_f32_e32 v129, v51
	v_cvt_pk_bf16_f32 v118, v126, v127
	v_pk_fma_f32 v[50:51], v[54:55], s[12:13], v[104:105] op_sel_hi:[1,0,0]
	v_exp_f32_e32 v130, v50
	v_exp_f32_e32 v131, v51
	v_cvt_pk_bf16_f32 v119, v128, v129
	v_pk_fma_f32 v[50:51], v[56:57], s[12:13], v[104:105] op_sel_hi:[1,0,0]
	v_exp_f32_e32 v56, v50
	v_exp_f32_e32 v57, v51
	v_cvt_pk_bf16_f32 v120, v130, v131
	v_cvt_pk_bf16_f32 v121, v56, v57
	s_waitcnt lgkmcnt(0)
	s_nop 0
	v_mfma_f32_32x32x16_bf16 v[18:33], v[216:219], v[118:121], v[18:33]
	s_waitcnt lgkmcnt(0)
	v_mfma_f32_32x32x16_bf16 v[2:17], v[220:223], v[118:121], v[2:17]
	v_add_f32_e64 v52, v126, 0
	v_add_f32_e64 v53, v127, 0
	v_add_f32_e64 v52, v128, v52
	v_add_f32_e64 v53, v129, v53
	v_add_f32_e64 v52, v130, v52
	v_add_f32_e64 v53, v131, v53
	v_pk_add_f32 v[118:119], v[56:57], v[52:53]
	v_pk_fma_f32 v[52:53], v[58:59], s[12:13], v[104:105] op_sel_hi:[1,0,0]
	v_exp_f32_e32 v120, v52
	v_exp_f32_e32 v121, v53
	v_pk_fma_f32 v[54:55], v[60:61], s[12:13], v[104:105] op_sel_hi:[1,0,0]
	v_exp_f32_e32 v60, v54
	v_exp_f32_e32 v61, v55
	v_cvt_pk_bf16_f32 v52, v120, v121
	v_pk_fma_f32 v[54:55], v[62:63], s[12:13], v[104:105] op_sel_hi:[1,0,0]
	v_exp_f32_e32 v62, v54
	v_exp_f32_e32 v63, v55
	v_cvt_pk_bf16_f32 v53, v60, v61
	v_pk_fma_f32 v[56:57], v[64:65], s[12:13], v[104:105] op_sel_hi:[1,0,0]
	v_exp_f32_e32 v64, v56
	v_exp_f32_e32 v65, v57
	v_cvt_pk_bf16_f32 v54, v62, v63
	v_cvt_pk_bf16_f32 v55, v64, v65
	s_nop 1
	v_mfma_f32_32x32x16_bf16 v[18:33], v[224:227], v[52:55], v[18:33]
	s_waitcnt lgkmcnt(0)
	v_mfma_f32_32x32x16_bf16 v[2:17], v[228:231], v[52:55], v[2:17]
	v_fma_f32 v54, v34, s12, v104
	v_fma_f32 v55, v35, s12, v104
	v_fma_f32 v56, v36, s12, v104
	v_fma_f32 v57, v37, s12, v104
	v_exp_f32_e32 v54, v54
	v_exp_f32_e32 v55, v55
	v_pk_add_f32 v[52:53], v[120:121], v[118:119]
	v_pk_add_f32 v[52:53], v[60:61], v[52:53]
	v_exp_f32_e32 v56, v56
	v_exp_f32_e32 v57, v57
	v_cvt_pk_bf16_f32 v34, v54, v55
	v_pk_add_f32 v[52:53], v[62:63], v[52:53]
	v_pk_add_f32 v[52:53], v[64:65], v[52:53]
	v_pk_fma_f32 v[36:37], v[38:39], s[12:13], v[104:105] op_sel_hi:[1,0,0]
	v_exp_f32_e32 v58, v36
	v_exp_f32_e32 v59, v37
	v_cvt_pk_bf16_f32 v35, v56, v57
	v_pk_fma_f32 v[38:39], v[40:41], s[12:13], v[104:105] op_sel_hi:[1,0,0]
	v_exp_f32_e32 v60, v38
	v_exp_f32_e32 v61, v39
	v_cvt_pk_bf16_f32 v36, v58, v59
	v_cvt_pk_bf16_f32 v37, v60, v61
	s_waitcnt lgkmcnt(0)
	s_nop 0
	v_mfma_f32_32x32x16_bf16 v[18:33], v[232:235], v[34:37], v[18:33]
	s_waitcnt lgkmcnt(0)
	v_mfma_f32_32x32x16_bf16 v[2:17], v[236:239], v[34:37], v[2:17]
	v_add_f32_e64 v34, v54, v52
	v_add_f32_e64 v35, v55, v53
	v_add_f32_e64 v34, v56, v34
	v_add_f32_e64 v35, v57, v35
	v_add_f32_e64 v34, v58, v34
	v_add_f32_e64 v35, v59, v35
	v_pk_add_f32 v[52:53], v[60:61], v[34:35]
	v_pk_fma_f32 v[34:35], v[42:43], s[12:13], v[104:105] op_sel_hi:[1,0,0]
	v_exp_f32_e32 v42, v34
	v_exp_f32_e32 v43, v35
	v_pk_fma_f32 v[36:37], v[44:45], s[12:13], v[104:105] op_sel_hi:[1,0,0]
	v_exp_f32_e32 v44, v36
	v_exp_f32_e32 v45, v37
	v_cvt_pk_bf16_f32 v34, v42, v43
	v_pk_fma_f32 v[36:37], v[46:47], s[12:13], v[104:105] op_sel_hi:[1,0,0]
	v_exp_f32_e32 v46, v36
	v_exp_f32_e32 v47, v37
	v_cvt_pk_bf16_f32 v35, v44, v45
	v_pk_fma_f32 v[38:39], v[48:49], s[12:13], v[104:105] op_sel_hi:[1,0,0]
	v_exp_f32_e32 v48, v38
	v_exp_f32_e32 v49, v39
	v_cvt_pk_bf16_f32 v36, v46, v47
	v_cvt_pk_bf16_f32 v37, v48, v49
	s_waitcnt lgkmcnt(0)
	s_nop 0
	v_mfma_f32_32x32x16_bf16 v[18:33], v[240:243], v[34:37], v[18:33]
	s_waitcnt lgkmcnt(0)
	v_mfma_f32_32x32x16_bf16 v[2:17], v[244:247], v[34:37], v[2:17]
	v_add_f32_e64 v34, v42, v52
	v_add_f32_e64 v35, v43, v53
	v_add_f32_e64 v34, v44, v34
	v_add_f32_e64 v35, v45, v35
	v_add_f32_e64 v34, v46, v34
	v_add_f32_e64 v35, v47, v35
	v_pk_add_f32 v[34:35], v[48:49], v[34:35]
	v_add_f32_e32 v34, v34, v35
	ds_bpermute_b32 v35, v117, v34
	s_cmp_ge_u32 s16, s19
	s_cbranch_scc1 .Ldma_f_mla1
	s_add_i32 s98, s6, 0xffffa800
	s_cmp_lg_u32 s22, 0
	s_cselect_b32 s98, s98, 0x10800
	v_readfirstlane_b32 s99, v107
	s_add_i32 m0, s99, s98
	v_readfirstlane_b32 s99, v93
	global_load_lds_dwordx4 v[102:103], off
	s_add_i32 m0, s99, s98
	v_readfirstlane_b32 s99, v108
	global_load_lds_dwordx4 v[100:101], off
	s_add_i32 m0, s99, s98
	s_nop 0
	global_load_lds_dwordx4 v[98:99], off

; template <int N> DI void wait_vmcnt() { asm volatile("s_waitcnt vmcnt(%0)" ::"n"(N) : "memory"); }
;     ...
;   asm volatile("s_waitcnt vmcnt(0)" ::: "memory");
; #pragma unroll
;   for (int t = 0; t < NST - 1; ++t)
;     if (t < ntile) FA_ISSUE(t, t)
;   int stage = 0;
;   for (int t = 0; t < ntile; ++t) {
;     int ahead = ((ntile < t + NST - 1) ? ntile : t + NST - 1) - (t + 1);
;     if (NST == 4 && ahead >= 2) wait_vmcnt<2 * NI>();
;     else if (ahead >= 1) wait_vmcnt<NI>();
;     else wait_vmcnt<0>();
;     raw_barrier();
;     if (t + NST - 1 < ntile) {
;       const int sn = (stage == 0) ? NST - 1 : stage - 1;
;       FA_ISSUE(t + NST - 1, sn)
;     }
.LBB0_363:
	s_or_b64 exec, exec, s[10:11]
	s_cmp_ge_u32 s16, s19
	s_cbranch_scc1 .Ldma_skip_mla1
	s_add_i32 s98, s6, 0xffffa800
	s_cmp_lg_u32 s22, 0
	s_cselect_b32 s98, s98, 0x10800
	v_readfirstlane_b32 s99, v107
	s_add_i32 m0, s99, s98
	v_readfirstlane_b32 s99, v93
	global_load_lds_dwordx4 v[102:103], off
	s_add_i32 m0, s99, s98
	v_readfirstlane_b32 s99, v108
	global_load_lds_dwordx4 v[100:101], off
	s_add_i32 m0, s99, s98
	s_nop 0
	global_load_lds_dwordx4 v[98:99], off

; #define MFMA(a, b, c) __builtin_amdgcn_mfma_f32_32x32x16_bf16((a), (b), (c), 0, 0, 0)
;     ...
;   float mc = m * c2;
;   if (MODE == 2) mc = selbit ? mc : 1e30f;
;   const f32x2v c2v = {c2, c2}, mcv = {-mc, -mc};
;   f32x2v rs2 = {0.f, 0.f};
; #pragma unroll
;   for (int ks = 0; ks < 2; ++ks)
; #pragma unroll
;     for (int st = 0; st < 2; ++st) {
;       union { unsigned u[4]; bf16x8 v; } pf;
; #pragma unroll
;       for (int j = 0; j < 4; ++j) {
;         const int i0 = 8 * st + 2 * j;
;         f32x2v t = {S[ks][i0], S[ks][i0 + 1]};
;         t = __builtin_elementwise_fma(t, c2v, mcv);
;         f32x2v pv;
;         if (variant == 1) { pv = t; } else {
;         pv.x = __builtin_amdgcn_exp2f(t.x);
;         pv.y = __builtin_amdgcn_exp2f(t.y);
;         }
;         if (MODE != 0) {
;           if (need_mask) {
;             pv.x = (S[ks][i0] > -1e29f) ? pv.x : 0.f;
;             pv.y = (S[ks][i0 + 1] > -1e29f) ? pv.y : 0.f;
;           }
;         }
;         rs2 += pv;
;         pf.u[j] = __builtin_bit_cast(unsigned, __builtin_convertvector(pv, hwbf16x2));
;       }
; #pragma unroll
;       for (int d = 0; d < DV / 32; ++d) {
;         const char* vp = base + C::KBYTES + (d * 32 + lr) * C::VSTR + (ks * 32 + 16 * st + 4 * lh) * 2;
;         const s16x4 lo = *(const s16x4*)vp, hi = *(const s16x4*)(vp + 16);
;         const bf16x8 vf = __builtin_shufflevector(lo, hi, 0, 1, 2, 3, 4, 5, 6, 7);
;         O[d] = MFMA(vf, pf.v, O[d]);
;       }
;     }
.LBB0_424:
	s_cmp_eq_u64 s[8:9], 0
	s_cbranch_scc1 .Lfast_sel1
	v_mul_f32_e32 v110, 0xbe38aa3b, v110
	v_cndmask_b32_e64 v110, v208, v110, s[10:11]
	v_pk_fma_f32 v[120:121], v[82:83], s[96:97], v[110:111] op_sel_hi:[1,0,0]
	v_cmp_lt_f32_e32 vcc, s33, v82
	v_exp_f32_e32 v119, v120
	v_exp_f32_e32 v120, v121
	v_cndmask_b32_e32 v82, 0, v119, vcc
	v_cmp_lt_f32_e32 vcc, s33, v83
	v_cndmask_b32_e64 v128, v119, v82, s[8:9]
	s_nop 0
	v_cndmask_b32_e32 v83, 0, v120, vcc
	v_cndmask_b32_e64 v129, v120, v83, s[8:9]
	v_pk_fma_f32 v[82:83], v[84:85], s[96:97], v[110:111] op_sel_hi:[1,0,0]
	v_cmp_lt_f32_e32 vcc, s33, v84
	v_exp_f32_e32 v82, v82
	v_exp_f32_e32 v83, v83
	v_cvt_pk_bf16_f32 v120, v128, v129
	v_cndmask_b32_e32 v84, 0, v82, vcc
	v_cmp_lt_f32_e32 vcc, s33, v85
	v_cndmask_b32_e64 v152, v82, v84, s[8:9]
	s_nop 0
	v_cndmask_b32_e32 v85, 0, v83, vcc
	v_cndmask_b32_e64 v153, v83, v85, s[8:9]
	v_pk_fma_f32 v[82:83], v[86:87], s[96:97], v[110:111] op_sel_hi:[1,0,0]
	v_cmp_lt_f32_e32 vcc, s33, v86
	v_exp_f32_e32 v82, v82
	v_exp_f32_e32 v83, v83
	v_cvt_pk_bf16_f32 v121, v152, v153
	v_cndmask_b32_e32 v84, 0, v82, vcc
	v_cmp_lt_f32_e32 vcc, s33, v87
	v_cndmask_b32_e64 v154, v82, v84, s[8:9]
	s_nop 0
	v_cndmask_b32_e32 v85, 0, v83, vcc
	v_cndmask_b32_e64 v155, v83, v85, s[8:9]
	v_pk_fma_f32 v[82:83], v[88:89], s[96:97], v[110:111] op_sel_hi:[1,0,0]
	v_cmp_lt_f32_e32 vcc, s33, v88
	v_exp_f32_e32 v82, v82
	v_exp_f32_e32 v83, v83
	v_cvt_pk_bf16_f32 v122, v154, v155
	v_cndmask_b32_e32 v84, 0, v82, vcc
	v_cmp_lt_f32_e32 vcc, s33, v89
	v_cndmask_b32_e64 v88, v82, v84, s[8:9]
	s_nop 0
	v_cndmask_b32_e32 v85, 0, v83, vcc
	v_cndmask_b32_e64 v89, v83, v85, s[8:9]
	s_nop 0
	s_nop 0
	s_nop 0
	s_nop 0
	v_cvt_pk_bf16_f32 v123, v88, v89
	s_nop 0
	v_cmp_lt_f32_e32 vcc, s33, v90
	s_waitcnt lgkmcnt(0)
	v_mfma_f32_32x32x16_bf16 v[50:65], v[216:219], v[120:123], v[50:65]
	s_nop 0
	s_waitcnt lgkmcnt(0)
	v_mfma_f32_32x32x16_bf16 v[34:49], v[220:223], v[120:123], v[34:49]
	v_add_f32_e64 v84, v128, 0
	v_add_f32_e64 v85, v129, 0
	v_add_f32_e64 v84, v152, v84
	v_add_f32_e64 v85, v153, v85
	v_add_f32_e64 v84, v154, v84
	v_add_f32_e64 v85, v155, v85
	v_pk_add_f32 v[120:121], v[88:89], v[84:85]
	v_pk_fma_f32 v[84:85], v[90:91], s[96:97], v[110:111] op_sel_hi:[1,0,0]
	s_nop 0
	v_exp_f32_e32 v84, v84
	v_exp_f32_e32 v85, v85
	v_cndmask_b32_e32 v86, 0, v84, vcc
	v_cmp_lt_f32_e32 vcc, s33, v91
	v_cndmask_b32_e64 v122, v84, v86, s[8:9]
	s_nop 0
	v_cndmask_b32_e32 v87, 0, v85, vcc
	v_cndmask_b32_e64 v123, v85, v87, s[8:9]
	v_pk_fma_f32 v[86:87], v[92:93], s[96:97], v[110:111] op_sel_hi:[1,0,0]
	v_cmp_lt_f32_e32 vcc, s33, v92
	v_exp_f32_e32 v85, v86
	v_exp_f32_e32 v86, v87
	v_cvt_pk_bf16_f32 v84, v122, v123
	v_cndmask_b32_e32 v87, 0, v85, vcc
	v_cmp_lt_f32_e32 vcc, s33, v93
	v_cndmask_b32_e64 v92, v85, v87, s[8:9]
	s_nop 0
	v_cndmask_b32_e32 v88, 0, v86, vcc
	v_cndmask_b32_e64 v93, v86, v88, s[8:9]
	v_pk_fma_f32 v[86:87], v[94:95], s[96:97], v[110:111] op_sel_hi:[1,0,0]
	v_cmp_lt_f32_e32 vcc, s33, v94
	v_exp_f32_e32 v86, v86
	v_exp_f32_e32 v87, v87
	v_cvt_pk_bf16_f32 v85, v92, v93
	v_cndmask_b32_e32 v88, 0, v86, vcc
	v_cmp_lt_f32_e32 vcc, s33, v95
	v_cndmask_b32_e64 v94, v86, v88, s[8:9]
	s_nop 0
	v_cndmask_b32_e32 v89, 0, v87, vcc
	v_cndmask_b32_e64 v95, v87, v89, s[8:9]
	v_pk_fma_f32 v[88:89], v[96:97], s[96:97], v[110:111] op_sel_hi:[1,0,0]
	v_cmp_lt_f32_e32 vcc, s33, v96
	v_exp_f32_e32 v87, v88
	v_exp_f32_e32 v88, v89
	v_cvt_pk_bf16_f32 v86, v94, v95
	v_cndmask_b32_e32 v89, 0, v87, vcc
	v_cmp_lt_f32_e32 vcc, s33, v97
	v_cndmask_b32_e64 v96, v87, v89, s[8:9]
	s_nop 0
	v_cndmask_b32_e32 v90, 0, v88, vcc
	v_cndmask_b32_e64 v97, v88, v90, s[8:9]
	s_nop 0
	v_cvt_pk_bf16_f32 v87, v96, v97
	v_cmp_lt_f32_e32 vcc, s33, v66
	s_nop 0
	v_mfma_f32_32x32x16_bf16 v[50:65], v[224:227], v[84:87], v[50:65]
	s_waitcnt lgkmcnt(0)
; #define MFMA(a, b, c) __builtin_amdgcn_mfma_f32_32x32x16_bf16((a), (b), (c), 0, 0, 0)
; template <int N> DI void wait_vmcnt() { asm volatile("s_waitcnt vmcnt(%0)" ::"n"(N) : "memory"); }
;     ...
; #pragma unroll
;       for (int j = 0; j < 4; ++j) {
;         const int i0 = 8 * st + 2 * j;
;         f32x2v t = {S[ks][i0], S[ks][i0 + 1]};
;         t = __builtin_elementwise_fma(t, c2v, mcv);
;         f32x2v pv;
;         if (variant == 1) { pv = t; } else {
;         pv.x = __builtin_amdgcn_exp2f(t.x);
;         pv.y = __builtin_amdgcn_exp2f(t.y);
;         }
;         if (MODE != 0) {
;           if (need_mask) {
;             pv.x = (S[ks][i0] > -1e29f) ? pv.x : 0.f;
;             pv.y = (S[ks][i0 + 1] > -1e29f) ? pv.y : 0.f;
;           }
;         }
;         rs2 += pv;
;         pf.u[j] = __builtin_bit_cast(unsigned, __builtin_convertvector(pv, hwbf16x2));
;       }
; #pragma unroll
;       for (int d = 0; d < DV / 32; ++d) {
;         const char* vp = base + C::KBYTES + (d * 32 + lr) * C::VSTR + (ks * 32 + 16 * st + 4 * lh) * 2;
;         const s16x4 lo = *(const s16x4*)vp, hi = *(const s16x4*)(vp + 16);
;         const bf16x8 vf = __builtin_shufflevector(lo, hi, 0, 1, 2, 3, 4, 5, 6, 7);
;         O[d] = MFMA(vf, pf.v, O[d]);
;       }
;     }
;   float rs = rs2.x + rs2.y;
;   rs += __shfl_xor(rs, 32);
;     ...
;   asm volatile("s_waitcnt vmcnt(0)" ::: "memory");
; #pragma unroll
;   for (int t = 0; t < NST - 1; ++t)
;     if (t < ntile) FA_ISSUE(t, t)
;   int stage = 0;
;   for (int t = 0; t < ntile; ++t) {
;     int ahead = ((ntile < t + NST - 1) ? ntile : t + NST - 1) - (t + 1);
;     if (NST == 4 && ahead >= 2) wait_vmcnt<2 * NI>();
;     else if (ahead >= 1) wait_vmcnt<NI>();
;     else wait_vmcnt<0>();
;     raw_barrier();
;     if (t + NST - 1 < ntile) {
;       const int sn = (stage == 0) ? NST - 1 : stage - 1;
;       FA_ISSUE(t + NST - 1, sn)
	v_mfma_f32_32x32x16_bf16 v[34:49], v[228:231], v[84:87], v[34:49]
	v_fma_f32 v86, v66, s96, v110
	v_fma_f32 v87, v67, s96, v110
	v_fma_f32 v88, v68, s96, v110
	v_fma_f32 v89, v69, s96, v110
	v_exp_f32_e32 v86, v86
	v_exp_f32_e32 v87, v87
	v_pk_add_f32 v[84:85], v[122:123], v[120:121]
	v_cndmask_b32_e32 v66, 0, v86, vcc
	v_cmp_lt_f32_e32 vcc, s33, v67
	v_pk_add_f32 v[84:85], v[92:93], v[84:85]
	v_cndmask_b32_e64 v86, v86, v66, s[8:9]
	v_cndmask_b32_e32 v67, 0, v87, vcc
	v_cndmask_b32_e64 v87, v87, v67, s[8:9]
	v_exp_f32_e32 v67, v88
	v_exp_f32_e32 v88, v89
	v_cmp_lt_f32_e32 vcc, s33, v68
	v_cvt_pk_bf16_f32 v66, v86, v87
	v_pk_add_f32 v[84:85], v[94:95], v[84:85]
	v_cndmask_b32_e32 v68, 0, v67, vcc
	v_cmp_lt_f32_e32 vcc, s33, v69
	v_pk_add_f32 v[84:85], v[96:97], v[84:85]
	s_nop 0
	v_cndmask_b32_e32 v69, 0, v88, vcc
	v_cndmask_b32_e64 v89, v88, v69, s[8:9]
	v_cndmask_b32_e64 v88, v67, v68, s[8:9]
	v_pk_fma_f32 v[68:69], v[70:71], s[96:97], v[110:111] op_sel_hi:[1,0,0]
	v_cmp_lt_f32_e32 vcc, s33, v70
	v_exp_f32_e32 v68, v68
	v_exp_f32_e32 v69, v69
	v_cvt_pk_bf16_f32 v67, v88, v89
	v_cndmask_b32_e32 v70, 0, v68, vcc
	v_cmp_lt_f32_e32 vcc, s33, v71
	v_cndmask_b32_e64 v90, v68, v70, s[8:9]
	s_nop 0
	v_cndmask_b32_e32 v71, 0, v69, vcc
	v_cndmask_b32_e64 v91, v69, v71, s[8:9]
	v_pk_fma_f32 v[70:71], v[72:73], s[96:97], v[110:111] op_sel_hi:[1,0,0]
	v_cmp_lt_f32_e32 vcc, s33, v72
	v_exp_f32_e32 v69, v70
	v_exp_f32_e32 v70, v71
	v_cvt_pk_bf16_f32 v68, v90, v91
	v_cndmask_b32_e32 v71, 0, v69, vcc
	v_cmp_lt_f32_e32 vcc, s33, v73
	v_cndmask_b32_e64 v92, v69, v71, s[8:9]
	s_nop 0
	v_cndmask_b32_e32 v72, 0, v70, vcc
	v_cndmask_b32_e64 v93, v70, v72, s[8:9]
	s_nop 0
	v_cvt_pk_bf16_f32 v69, v92, v93
	v_cmp_lt_f32_e32 vcc, s33, v74
	s_waitcnt lgkmcnt(0)
	v_mfma_f32_32x32x16_bf16 v[50:65], v[232:235], v[66:69], v[50:65]
	s_nop 0
	s_waitcnt lgkmcnt(0)
	v_mfma_f32_32x32x16_bf16 v[34:49], v[236:239], v[66:69], v[34:49]
	v_add_f32_e64 v66, v86, v84
	v_add_f32_e64 v67, v87, v85
	v_add_f32_e64 v66, v88, v66
	v_add_f32_e64 v67, v89, v67
	v_add_f32_e64 v66, v90, v66
	v_add_f32_e64 v67, v91, v67
	v_pk_add_f32 v[84:85], v[92:93], v[66:67]
	v_pk_fma_f32 v[66:67], v[74:75], s[96:97], v[110:111] op_sel_hi:[1,0,0]
	s_nop 0
	v_exp_f32_e32 v66, v66
	v_exp_f32_e32 v67, v67
	v_cndmask_b32_e32 v68, 0, v66, vcc
	v_cmp_lt_f32_e32 vcc, s33, v75
	v_cndmask_b32_e64 v74, v66, v68, s[8:9]
	s_nop 0
	v_cndmask_b32_e32 v69, 0, v67, vcc
	v_cndmask_b32_e64 v75, v67, v69, s[8:9]
	v_pk_fma_f32 v[68:69], v[76:77], s[96:97], v[110:111] op_sel_hi:[1,0,0]
	v_cmp_lt_f32_e32 vcc, s33, v76
	v_exp_f32_e32 v67, v68
	v_exp_f32_e32 v68, v69
	v_cvt_pk_bf16_f32 v66, v74, v75
	v_cndmask_b32_e32 v69, 0, v67, vcc
	v_cmp_lt_f32_e32 vcc, s33, v77
	v_cndmask_b32_e64 v76, v67, v69, s[8:9]
	s_nop 0
	v_cndmask_b32_e32 v70, 0, v68, vcc
	v_cndmask_b32_e64 v77, v68, v70, s[8:9]
	v_pk_fma_f32 v[68:69], v[78:79], s[96:97], v[110:111] op_sel_hi:[1,0,0]
	v_cmp_lt_f32_e32 vcc, s33, v78
	v_exp_f32_e32 v68, v68
	v_exp_f32_e32 v69, v69
	v_cvt_pk_bf16_f32 v67, v76, v77
	v_cndmask_b32_e32 v70, 0, v68, vcc
	v_cmp_lt_f32_e32 vcc, s33, v79
	v_cndmask_b32_e64 v78, v68, v70, s[8:9]
	s_nop 0
	v_cndmask_b32_e32 v71, 0, v69, vcc
	v_cndmask_b32_e64 v79, v69, v71, s[8:9]
	v_pk_fma_f32 v[70:71], v[80:81], s[96:97], v[110:111] op_sel_hi:[1,0,0]
	v_cmp_lt_f32_e32 vcc, s33, v80
	v_exp_f32_e32 v69, v70
	v_exp_f32_e32 v70, v71
	v_cvt_pk_bf16_f32 v68, v78, v79
	v_cndmask_b32_e32 v71, 0, v69, vcc
	v_cmp_lt_f32_e32 vcc, s33, v81
	v_cndmask_b32_e64 v80, v69, v71, s[8:9]
	s_nop 0
	v_cndmask_b32_e32 v72, 0, v70, vcc
	v_cndmask_b32_e64 v81, v70, v72, s[8:9]
	s_nop 0
	v_cvt_pk_bf16_f32 v69, v80, v81
	s_waitcnt lgkmcnt(0)
	s_nop 0
	v_mfma_f32_32x32x16_bf16 v[50:65], v[240:243], v[66:69], v[50:65]
	s_nop 0
	s_waitcnt lgkmcnt(0)
	v_mfma_f32_32x32x16_bf16 v[34:49], v[244:247], v[66:69], v[34:49]
	v_add_f32_e64 v66, v74, v84
	v_add_f32_e64 v67, v75, v85
	v_add_f32_e64 v66, v76, v66
	v_add_f32_e64 v67, v77, v67
	v_add_f32_e64 v66, v78, v66
	v_add_f32_e64 v67, v79, v67
	v_pk_add_f32 v[66:67], v[80:81], v[66:67]
	s_nop 0
	v_add_f32_e32 v66, v66, v67
	ds_bpermute_b32 v67, v165, v66
	s_add_i32 s98, s0, 3
	s_cmp_gt_u32 s98, s46
	s_cbranch_scc1 .Ldma_m_sel1
	s_add_i32 s98, s6, 0xffffb800
	s_cmp_lg_u32 s48, 0
	s_cselect_b32 s98, s98, 0xd800
	v_readfirstlane_b32 s99, v112
	s_add_i32 m0, s99, s98
	v_readfirstlane_b32 s99, v111
	global_load_lds_dwordx4 v[108:109], off
	s_add_i32 m0, s99, s98
	v_readfirstlane_b32 s99, v113
	global_load_lds_dwordx4 v[106:107], off
	s_add_i32 m0, s99, s98
	s_nop 0
	global_load_lds_dwordx4 v[104:105], off

; #define MFMA(a, b, c) __builtin_amdgcn_mfma_f32_32x32x16_bf16((a), (b), (c), 0, 0, 0)
; template <int N> DI void wait_vmcnt() { asm volatile("s_waitcnt vmcnt(%0)" ::"n"(N) : "memory"); }
;     ...
;   float mc = m * c2;
;   if (MODE == 2) mc = selbit ? mc : 1e30f;
;   const f32x2v c2v = {c2, c2}, mcv = {-mc, -mc};
;   f32x2v rs2 = {0.f, 0.f};
; #pragma unroll
;   for (int ks = 0; ks < 2; ++ks)
; #pragma unroll
;     for (int st = 0; st < 2; ++st) {
;       union { unsigned u[4]; bf16x8 v; } pf;
; #pragma unroll
;       for (int j = 0; j < 4; ++j) {
;         const int i0 = 8 * st + 2 * j;
;         f32x2v t = {S[ks][i0], S[ks][i0 + 1]};
;         t = __builtin_elementwise_fma(t, c2v, mcv);
;         f32x2v pv;
;         if (variant == 1) { pv = t; } else {
;         pv.x = __builtin_amdgcn_exp2f(t.x);
;         pv.y = __builtin_amdgcn_exp2f(t.y);
;         }
;         if (MODE != 0) {
;           if (need_mask) {
;             pv.x = (S[ks][i0] > -1e29f) ? pv.x : 0.f;
;             pv.y = (S[ks][i0 + 1] > -1e29f) ? pv.y : 0.f;
;           }
;         }
;         rs2 += pv;
;         pf.u[j] = __builtin_bit_cast(unsigned, __builtin_convertvector(pv, hwbf16x2));
;       }
; #pragma unroll
;       for (int d = 0; d < DV / 32; ++d) {
;         const char* vp = base + C::KBYTES + (d * 32 + lr) * C::VSTR + (ks * 32 + 16 * st + 4 * lh) * 2;
;         const s16x4 lo = *(const s16x4*)vp, hi = *(const s16x4*)(vp + 16);
;         const bf16x8 vf = __builtin_shufflevector(lo, hi, 0, 1, 2, 3, 4, 5, 6, 7);
;         O[d] = MFMA(vf, pf.v, O[d]);
;       }
;     }
;   float rs = rs2.x + rs2.y;
;   rs += __shfl_xor(rs, 32);
;     ...
;   asm volatile("s_waitcnt vmcnt(0)" ::: "memory");
; #pragma unroll
;   for (int t = 0; t < NST - 1; ++t)
;     if (t < ntile) FA_ISSUE(t, t)
;   int stage = 0;
;   for (int t = 0; t < ntile; ++t) {
;     int ahead = ((ntile < t + NST - 1) ? ntile : t + NST - 1) - (t + 1);
;     if (NST == 4 && ahead >= 2) wait_vmcnt<2 * NI>();
;     else if (ahead >= 1) wait_vmcnt<NI>();
;     else wait_vmcnt<0>();
;     raw_barrier();
;     if (t + NST - 1 < ntile) {
;       const int sn = (stage == 0) ? NST - 1 : stage - 1;
;       FA_ISSUE(t + NST - 1, sn)
.Lfast_sel1:
	v_mul_f32_e32 v110, 0xbe38aa3b, v110
	v_cndmask_b32_e64 v110, v208, v110, s[10:11]
	v_pk_fma_f32 v[120:121], v[82:83], s[96:97], v[110:111] op_sel_hi:[1,0,0]
	v_exp_f32_e32 v128, v120
	v_exp_f32_e32 v129, v121
	v_pk_fma_f32 v[82:83], v[84:85], s[96:97], v[110:111] op_sel_hi:[1,0,0]
	v_exp_f32_e32 v152, v82
	v_exp_f32_e32 v153, v83
	v_cvt_pk_bf16_f32 v120, v128, v129
	v_pk_fma_f32 v[82:83], v[86:87], s[96:97], v[110:111] op_sel_hi:[1,0,0]
	v_exp_f32_e32 v154, v82
	v_exp_f32_e32 v155, v83
	v_cvt_pk_bf16_f32 v121, v152, v153
	v_pk_fma_f32 v[82:83], v[88:89], s[96:97], v[110:111] op_sel_hi:[1,0,0]
	v_exp_f32_e32 v88, v82
	v_exp_f32_e32 v89, v83
	v_cvt_pk_bf16_f32 v122, v154, v155
	v_cvt_pk_bf16_f32 v123, v88, v89
	s_waitcnt lgkmcnt(0)
	s_nop 0
	v_mfma_f32_32x32x16_bf16 v[50:65], v[216:219], v[120:123], v[50:65]
	s_waitcnt lgkmcnt(0)
	v_mfma_f32_32x32x16_bf16 v[34:49], v[220:223], v[120:123], v[34:49]
	v_add_f32_e64 v84, v128, 0
	v_add_f32_e64 v85, v129, 0
	v_add_f32_e64 v84, v152, v84
	v_add_f32_e64 v85, v153, v85
	v_add_f32_e64 v84, v154, v84
	v_add_f32_e64 v85, v155, v85
	v_pk_add_f32 v[120:121], v[88:89], v[84:85]
	v_pk_fma_f32 v[84:85], v[90:91], s[96:97], v[110:111] op_sel_hi:[1,0,0]
	v_exp_f32_e32 v122, v84
	v_exp_f32_e32 v123, v85
	v_pk_fma_f32 v[86:87], v[92:93], s[96:97], v[110:111] op_sel_hi:[1,0,0]
	v_exp_f32_e32 v92, v86
	v_exp_f32_e32 v93, v87
	v_cvt_pk_bf16_f32 v84, v122, v123
	v_pk_fma_f32 v[86:87], v[94:95], s[96:97], v[110:111] op_sel_hi:[1,0,0]
	v_exp_f32_e32 v94, v86
	v_exp_f32_e32 v95, v87
	v_cvt_pk_bf16_f32 v85, v92, v93
	v_pk_fma_f32 v[88:89], v[96:97], s[96:97], v[110:111] op_sel_hi:[1,0,0]
	v_exp_f32_e32 v96, v88
	v_exp_f32_e32 v97, v89
	v_cvt_pk_bf16_f32 v86, v94, v95
	v_cvt_pk_bf16_f32 v87, v96, v97
	s_nop 1
	v_mfma_f32_32x32x16_bf16 v[50:65], v[224:227], v[84:87], v[50:65]
	s_waitcnt lgkmcnt(0)
	v_mfma_f32_32x32x16_bf16 v[34:49], v[228:231], v[84:87], v[34:49]
	v_fma_f32 v86, v66, s96, v110
	v_fma_f32 v87, v67, s96, v110
	v_fma_f32 v88, v68, s96, v110
	v_fma_f32 v89, v69, s96, v110
	v_exp_f32_e32 v86, v86
	v_exp_f32_e32 v87, v87
	v_pk_add_f32 v[84:85], v[122:123], v[120:121]
	v_pk_add_f32 v[84:85], v[92:93], v[84:85]
	v_exp_f32_e32 v88, v88
	v_exp_f32_e32 v89, v89
	v_cvt_pk_bf16_f32 v66, v86, v87
	v_pk_add_f32 v[84:85], v[94:95], v[84:85]
	v_pk_add_f32 v[84:85], v[96:97], v[84:85]
	v_pk_fma_f32 v[68:69], v[70:71], s[96:97], v[110:111] op_sel_hi:[1,0,0]
	v_exp_f32_e32 v90, v68
	v_exp_f32_e32 v91, v69
	v_cvt_pk_bf16_f32 v67, v88, v89
	v_pk_fma_f32 v[70:71], v[72:73], s[96:97], v[110:111] op_sel_hi:[1,0,0]
	v_exp_f32_e32 v92, v70
	v_exp_f32_e32 v93, v71
	v_cvt_pk_bf16_f32 v68, v90, v91
	v_cvt_pk_bf16_f32 v69, v92, v93
	s_waitcnt lgkmcnt(0)
	s_nop 0
	v_mfma_f32_32x32x16_bf16 v[50:65], v[232:235], v[66:69], v[50:65]
	s_waitcnt lgkmcnt(0)
	v_mfma_f32_32x32x16_bf16 v[34:49], v[236:239], v[66:69], v[34:49]
	v_add_f32_e64 v66, v86, v84
	v_add_f32_e64 v67, v87, v85
	v_add_f32_e64 v66, v88, v66
	v_add_f32_e64 v67, v89, v67
	v_add_f32_e64 v66, v90, v66
	v_add_f32_e64 v67, v91, v67
	v_pk_add_f32 v[84:85], v[92:93], v[66:67]
	v_pk_fma_f32 v[66:67], v[74:75], s[96:97], v[110:111] op_sel_hi:[1,0,0]
	v_exp_f32_e32 v74, v66
	v_exp_f32_e32 v75, v67
	v_pk_fma_f32 v[68:69], v[76:77], s[96:97], v[110:111] op_sel_hi:[1,0,0]
	v_exp_f32_e32 v76, v68
	v_exp_f32_e32 v77, v69
	v_cvt_pk_bf16_f32 v66, v74, v75
	v_pk_fma_f32 v[68:69], v[78:79], s[96:97], v[110:111] op_sel_hi:[1,0,0]
	v_exp_f32_e32 v78, v68
	v_exp_f32_e32 v79, v69
	v_cvt_pk_bf16_f32 v67, v76, v77
	v_pk_fma_f32 v[70:71], v[80:81], s[96:97], v[110:111] op_sel_hi:[1,0,0]
	v_exp_f32_e32 v80, v70
	v_exp_f32_e32 v81, v71
	v_cvt_pk_bf16_f32 v68, v78, v79
	v_cvt_pk_bf16_f32 v69, v80, v81
	s_waitcnt lgkmcnt(0)
	s_nop 0
	v_mfma_f32_32x32x16_bf16 v[50:65], v[240:243], v[66:69], v[50:65]
	s_waitcnt lgkmcnt(0)
	v_mfma_f32_32x32x16_bf16 v[34:49], v[244:247], v[66:69], v[34:49]
	v_add_f32_e64 v66, v74, v84
	v_add_f32_e64 v67, v75, v85
	v_add_f32_e64 v66, v76, v66
	v_add_f32_e64 v67, v77, v67
	v_add_f32_e64 v66, v78, v66
	v_add_f32_e64 v67, v79, v67
	v_pk_add_f32 v[66:67], v[80:81], v[66:67]
	v_add_f32_e32 v66, v66, v67
	ds_bpermute_b32 v67, v165, v66
	s_add_i32 s98, s0, 3
	s_cmp_gt_u32 s98, s46
	s_cbranch_scc1 .Ldma_f_sel1
	s_add_i32 s98, s6, 0xffffb800
	s_cmp_lg_u32 s48, 0
	s_cselect_b32 s98, s98, 0xd800
	v_readfirstlane_b32 s99, v112
	s_add_i32 m0, s99, s98
	v_readfirstlane_b32 s99, v111
	global_load_lds_dwordx4 v[108:109], off
	s_add_i32 m0, s99, s98
	v_readfirstlane_b32 s99, v113
	global_load_lds_dwordx4 v[106:107], off
	s_add_i32 m0, s99, s98
	s_nop 0
	global_load_lds_dwordx4 v[104:105], off

; template <int N> DI void wait_vmcnt() { asm volatile("s_waitcnt vmcnt(%0)" ::"n"(N) : "memory"); }
;     ...
;   asm volatile("s_waitcnt vmcnt(0)" ::: "memory");
; #pragma unroll
;   for (int t = 0; t < NST - 1; ++t)
;     if (t < ntile) FA_ISSUE(t, t)
;   int stage = 0;
;   for (int t = 0; t < ntile; ++t) {
;     int ahead = ((ntile < t + NST - 1) ? ntile : t + NST - 1) - (t + 1);
;     if (NST == 4 && ahead >= 2) wait_vmcnt<2 * NI>();
;     else if (ahead >= 1) wait_vmcnt<NI>();
;     else wait_vmcnt<0>();
;     raw_barrier();
;     if (t + NST - 1 < ntile) {
;       const int sn = (stage == 0) ? NST - 1 : stage - 1;
;       FA_ISSUE(t + NST - 1, sn)
;     }
.LBB0_425:
	s_add_i32 s98, s0, 3
	s_cmp_gt_u32 s98, s46
	s_cbranch_scc1 .Ldma_skip_sel1
	s_add_i32 s98, s6, 0xffffb800
	s_cmp_lg_u32 s48, 0
	s_cselect_b32 s98, s98, 0xd800
	v_readfirstlane_b32 s99, v112
	s_add_i32 m0, s99, s98
	v_readfirstlane_b32 s99, v111
	global_load_lds_dwordx4 v[108:109], off
	s_add_i32 m0, s99, s98
	v_readfirstlane_b32 s99, v113
	global_load_lds_dwordx4 v[106:107], off
	s_add_i32 m0, s99, s98
	s_nop 0
	global_load_lds_dwordx4 v[104:105], off

; #define MFMA(a, b, c) __builtin_amdgcn_mfma_f32_32x32x16_bf16((a), (b), (c), 0, 0, 0)
;     ...
;   float mc = m * c2;
;   if (MODE == 2) mc = selbit ? mc : 1e30f;
;   const f32x2v c2v = {c2, c2}, mcv = {-mc, -mc};
;   f32x2v rs2 = {0.f, 0.f};
; #pragma unroll
;   for (int ks = 0; ks < 2; ++ks)
; #pragma unroll
;     for (int st = 0; st < 2; ++st) {
;       union { unsigned u[4]; bf16x8 v; } pf;
; #pragma unroll
;       for (int j = 0; j < 4; ++j) {
;         const int i0 = 8 * st + 2 * j;
;         f32x2v t = {S[ks][i0], S[ks][i0 + 1]};
;         t = __builtin_elementwise_fma(t, c2v, mcv);
;         f32x2v pv;
;         if (variant == 1) { pv = t; } else {
;         pv.x = __builtin_amdgcn_exp2f(t.x);
;         pv.y = __builtin_amdgcn_exp2f(t.y);
;         }
;         if (MODE != 0) {
;           if (need_mask) {
;             pv.x = (S[ks][i0] > -1e29f) ? pv.x : 0.f;
;             pv.y = (S[ks][i0 + 1] > -1e29f) ? pv.y : 0.f;
;           }
;         }
;         rs2 += pv;
;         pf.u[j] = __builtin_bit_cast(unsigned, __builtin_convertvector(pv, hwbf16x2));
;       }
; #pragma unroll
;       for (int d = 0; d < DV / 32; ++d) {
;         const char* vp = base + C::KBYTES + (d * 32 + lr) * C::VSTR + (ks * 32 + 16 * st + 4 * lh) * 2;
;         const s16x4 lo = *(const s16x4*)vp, hi = *(const s16x4*)(vp + 16);
;         const bf16x8 vf = __builtin_shufflevector(lo, hi, 0, 1, 2, 3, 4, 5, 6, 7);
;         O[d] = MFMA(vf, pf.v, O[d]);
;       }
;     }
.LBB0_455:
	s_cmp_eq_u64 s[8:9], 0
	s_cbranch_scc1 .Lfast_win1
	v_mul_f32_e32 v162, 0xbe38aa3b, v162
	v_pk_fma_f32 v[180:181], v[114:115], s[96:97], v[162:163] op_sel_hi:[1,0,0]
	v_cmp_lt_f32_e32 vcc, s33, v114
	v_exp_f32_e32 v179, v180
	v_exp_f32_e32 v180, v181
	v_cndmask_b32_e32 v114, 0, v179, vcc
	v_cmp_lt_f32_e32 vcc, s33, v115
	v_cndmask_b32_e64 v188, v179, v114, s[8:9]
	s_nop 0
	v_cndmask_b32_e32 v115, 0, v180, vcc
	v_cndmask_b32_e64 v189, v180, v115, s[8:9]
	v_pk_fma_f32 v[114:115], v[116:117], s[96:97], v[162:163] op_sel_hi:[1,0,0]
	v_cmp_lt_f32_e32 vcc, s33, v116
	v_exp_f32_e32 v114, v114
	v_exp_f32_e32 v115, v115
	v_cvt_pk_bf16_f32 v180, v188, v189
	v_cndmask_b32_e32 v116, 0, v114, vcc
	v_cmp_lt_f32_e32 vcc, s33, v117
	v_cndmask_b32_e64 v190, v114, v116, s[8:9]
	s_nop 0
	v_cndmask_b32_e32 v117, 0, v115, vcc
	v_cndmask_b32_e64 v191, v115, v117, s[8:9]
	v_pk_fma_f32 v[114:115], v[118:119], s[96:97], v[162:163] op_sel_hi:[1,0,0]
	v_cmp_lt_f32_e32 vcc, s33, v118
	v_exp_f32_e32 v114, v114
	v_exp_f32_e32 v115, v115
	v_cvt_pk_bf16_f32 v181, v190, v191
	v_cndmask_b32_e32 v116, 0, v114, vcc
	v_cmp_lt_f32_e32 vcc, s33, v119
	v_cndmask_b32_e64 v192, v114, v116, s[8:9]
	s_nop 0
	v_cndmask_b32_e32 v117, 0, v115, vcc
	v_cndmask_b32_e64 v193, v115, v117, s[8:9]
	v_pk_fma_f32 v[114:115], v[120:121], s[96:97], v[162:163] op_sel_hi:[1,0,0]
	v_cmp_lt_f32_e32 vcc, s33, v120
	v_exp_f32_e32 v114, v114
	v_exp_f32_e32 v115, v115
	v_cvt_pk_bf16_f32 v182, v192, v193
	v_cndmask_b32_e32 v116, 0, v114, vcc
	v_cmp_lt_f32_e32 vcc, s33, v121
	v_cndmask_b32_e64 v120, v114, v116, s[8:9]
	s_nop 0
	v_cndmask_b32_e32 v117, 0, v115, vcc
	v_cndmask_b32_e64 v121, v115, v117, s[8:9]
	s_nop 0
	s_nop 0
	s_nop 0
	s_nop 0
	v_cvt_pk_bf16_f32 v183, v120, v121
	s_nop 0
	v_cmp_lt_f32_e32 vcc, s33, v122
	s_waitcnt lgkmcnt(0)
	v_mfma_f32_32x32x16_bf16 v[82:97], v[216:219], v[180:183], v[82:97]
	s_nop 0
	s_waitcnt lgkmcnt(0)
	v_mfma_f32_32x32x16_bf16 v[66:81], v[220:223], v[180:183], v[66:81]
	v_add_f32_e64 v116, v188, 0
	v_add_f32_e64 v117, v189, 0
	v_add_f32_e64 v116, v190, v116
	v_add_f32_e64 v117, v191, v117
	v_add_f32_e64 v116, v192, v116
	v_add_f32_e64 v117, v193, v117
	v_pk_add_f32 v[180:181], v[120:121], v[116:117]
	v_pk_fma_f32 v[116:117], v[122:123], s[96:97], v[162:163] op_sel_hi:[1,0,0]
	s_nop 0
	v_exp_f32_e32 v116, v116
	v_exp_f32_e32 v117, v117
	v_cndmask_b32_e32 v118, 0, v116, vcc
	v_cmp_lt_f32_e32 vcc, s33, v123
	v_cndmask_b32_e64 v182, v116, v118, s[8:9]
	s_nop 0
	v_cndmask_b32_e32 v119, 0, v117, vcc
	v_cndmask_b32_e64 v183, v117, v119, s[8:9]
	v_pk_fma_f32 v[118:119], v[124:125], s[96:97], v[162:163] op_sel_hi:[1,0,0]
	v_cmp_lt_f32_e32 vcc, s33, v124
	v_exp_f32_e32 v117, v118
	v_exp_f32_e32 v118, v119
	v_cvt_pk_bf16_f32 v116, v182, v183
	v_cndmask_b32_e32 v119, 0, v117, vcc
	v_cmp_lt_f32_e32 vcc, s33, v125
	v_cndmask_b32_e64 v124, v117, v119, s[8:9]
	s_nop 0
	v_cndmask_b32_e32 v120, 0, v118, vcc
	v_cndmask_b32_e64 v125, v118, v120, s[8:9]
	v_pk_fma_f32 v[118:119], v[126:127], s[96:97], v[162:163] op_sel_hi:[1,0,0]
	v_cmp_lt_f32_e32 vcc, s33, v126
	v_exp_f32_e32 v118, v118
	v_exp_f32_e32 v119, v119
	v_cvt_pk_bf16_f32 v117, v124, v125
	v_cndmask_b32_e32 v120, 0, v118, vcc
	v_cmp_lt_f32_e32 vcc, s33, v127
	v_cndmask_b32_e64 v126, v118, v120, s[8:9]
	s_nop 0
	v_cndmask_b32_e32 v121, 0, v119, vcc
	v_cndmask_b32_e64 v127, v119, v121, s[8:9]
	v_pk_fma_f32 v[120:121], v[128:129], s[96:97], v[162:163] op_sel_hi:[1,0,0]
	v_cmp_lt_f32_e32 vcc, s33, v128
	v_exp_f32_e32 v119, v120
	v_exp_f32_e32 v120, v121
	v_cvt_pk_bf16_f32 v118, v126, v127
	v_cndmask_b32_e32 v121, 0, v119, vcc
	v_cmp_lt_f32_e32 vcc, s33, v129
	v_cndmask_b32_e64 v128, v119, v121, s[8:9]
	s_nop 0
	v_cndmask_b32_e32 v122, 0, v120, vcc
	v_cndmask_b32_e64 v129, v120, v122, s[8:9]
	s_nop 0
	v_cvt_pk_bf16_f32 v119, v128, v129
	v_cmp_lt_f32_e32 vcc, s33, v98
	s_nop 0
	v_mfma_f32_32x32x16_bf16 v[82:97], v[224:227], v[116:119], v[82:97]
	s_waitcnt lgkmcnt(0)
; #define MFMA(a, b, c) __builtin_amdgcn_mfma_f32_32x32x16_bf16((a), (b), (c), 0, 0, 0)
; template <int N> DI void wait_vmcnt() { asm volatile("s_waitcnt vmcnt(%0)" ::"n"(N) : "memory"); }
;     ...
; #pragma unroll
;       for (int j = 0; j < 4; ++j) {
;         const int i0 = 8 * st + 2 * j;
;         f32x2v t = {S[ks][i0], S[ks][i0 + 1]};
;         t = __builtin_elementwise_fma(t, c2v, mcv);
;         f32x2v pv;
;         if (variant == 1) { pv = t; } else {
;         pv.x = __builtin_amdgcn_exp2f(t.x);
;         pv.y = __builtin_amdgcn_exp2f(t.y);
;         }
;         if (MODE != 0) {
;           if (need_mask) {
;             pv.x = (S[ks][i0] > -1e29f) ? pv.x : 0.f;
;             pv.y = (S[ks][i0 + 1] > -1e29f) ? pv.y : 0.f;
;           }
;         }
;         rs2 += pv;
;         pf.u[j] = __builtin_bit_cast(unsigned, __builtin_convertvector(pv, hwbf16x2));
;       }
; #pragma unroll
;       for (int d = 0; d < DV / 32; ++d) {
;         const char* vp = base + C::KBYTES + (d * 32 + lr) * C::VSTR + (ks * 32 + 16 * st + 4 * lh) * 2;
;         const s16x4 lo = *(const s16x4*)vp, hi = *(const s16x4*)(vp + 16);
;         const bf16x8 vf = __builtin_shufflevector(lo, hi, 0, 1, 2, 3, 4, 5, 6, 7);
;         O[d] = MFMA(vf, pf.v, O[d]);
;       }
;     }
;   float rs = rs2.x + rs2.y;
;   rs += __shfl_xor(rs, 32);
;     ...
;   asm volatile("s_waitcnt vmcnt(0)" ::: "memory");
; #pragma unroll
;   for (int t = 0; t < NST - 1; ++t)
;     if (t < ntile) FA_ISSUE(t, t)
;   int stage = 0;
;   for (int t = 0; t < ntile; ++t) {
;     int ahead = ((ntile < t + NST - 1) ? ntile : t + NST - 1) - (t + 1);
;     if (NST == 4 && ahead >= 2) wait_vmcnt<2 * NI>();
;     else if (ahead >= 1) wait_vmcnt<NI>();
;     else wait_vmcnt<0>();
;     raw_barrier();
;     if (t + NST - 1 < ntile) {
;       const int sn = (stage == 0) ? NST - 1 : stage - 1;
;       FA_ISSUE(t + NST - 1, sn)
	v_mfma_f32_32x32x16_bf16 v[66:81], v[228:231], v[116:119], v[66:81]
	v_fma_f32 v118, v98, s96, v162
	v_fma_f32 v119, v99, s96, v162
	v_fma_f32 v120, v100, s96, v162
	v_fma_f32 v121, v101, s96, v162
	v_exp_f32_e32 v118, v118
	v_exp_f32_e32 v119, v119
	v_pk_add_f32 v[116:117], v[182:183], v[180:181]
	v_cndmask_b32_e32 v98, 0, v118, vcc
	v_cmp_lt_f32_e32 vcc, s33, v99
	v_pk_add_f32 v[116:117], v[124:125], v[116:117]
	v_cndmask_b32_e64 v118, v118, v98, s[8:9]
	v_cndmask_b32_e32 v99, 0, v119, vcc
	v_cndmask_b32_e64 v119, v119, v99, s[8:9]
	v_exp_f32_e32 v99, v120
	v_exp_f32_e32 v120, v121
	v_cmp_lt_f32_e32 vcc, s33, v100
	v_cvt_pk_bf16_f32 v98, v118, v119
	v_pk_add_f32 v[116:117], v[126:127], v[116:117]
	v_cndmask_b32_e32 v100, 0, v99, vcc
	v_cmp_lt_f32_e32 vcc, s33, v101
	v_pk_add_f32 v[116:117], v[128:129], v[116:117]
	s_nop 0
	v_cndmask_b32_e32 v101, 0, v120, vcc
	v_cndmask_b32_e64 v121, v120, v101, s[8:9]
	v_cndmask_b32_e64 v120, v99, v100, s[8:9]
	v_pk_fma_f32 v[100:101], v[102:103], s[96:97], v[162:163] op_sel_hi:[1,0,0]
	v_cmp_lt_f32_e32 vcc, s33, v102
	v_exp_f32_e32 v100, v100
	v_exp_f32_e32 v101, v101
	v_cvt_pk_bf16_f32 v99, v120, v121
	v_cndmask_b32_e32 v102, 0, v100, vcc
	v_cmp_lt_f32_e32 vcc, s33, v103
	v_cndmask_b32_e64 v122, v100, v102, s[8:9]
	s_nop 0
	v_cndmask_b32_e32 v103, 0, v101, vcc
	v_cndmask_b32_e64 v123, v101, v103, s[8:9]
	v_pk_fma_f32 v[102:103], v[104:105], s[96:97], v[162:163] op_sel_hi:[1,0,0]
	v_cmp_lt_f32_e32 vcc, s33, v104
	v_exp_f32_e32 v101, v102
	v_exp_f32_e32 v102, v103
	v_cvt_pk_bf16_f32 v100, v122, v123
	v_cndmask_b32_e32 v103, 0, v101, vcc
	v_cmp_lt_f32_e32 vcc, s33, v105
	v_cndmask_b32_e64 v124, v101, v103, s[8:9]
	s_nop 0
	v_cndmask_b32_e32 v104, 0, v102, vcc
	v_cndmask_b32_e64 v125, v102, v104, s[8:9]
	s_nop 0
	v_cvt_pk_bf16_f32 v101, v124, v125
	v_cmp_lt_f32_e32 vcc, s33, v106
	s_waitcnt lgkmcnt(0)
	v_mfma_f32_32x32x16_bf16 v[82:97], v[232:235], v[98:101], v[82:97]
	s_nop 0
	s_waitcnt lgkmcnt(0)
	v_mfma_f32_32x32x16_bf16 v[66:81], v[236:239], v[98:101], v[66:81]
	v_add_f32_e64 v98, v118, v116
	v_add_f32_e64 v99, v119, v117
	v_add_f32_e64 v98, v120, v98
	v_add_f32_e64 v99, v121, v99
	v_add_f32_e64 v98, v122, v98
	v_add_f32_e64 v99, v123, v99
	v_pk_add_f32 v[116:117], v[124:125], v[98:99]
	v_pk_fma_f32 v[98:99], v[106:107], s[96:97], v[162:163] op_sel_hi:[1,0,0]
	s_nop 0
	v_exp_f32_e32 v98, v98
	v_exp_f32_e32 v99, v99
	v_cndmask_b32_e32 v100, 0, v98, vcc
	v_cmp_lt_f32_e32 vcc, s33, v107
	v_cndmask_b32_e64 v106, v98, v100, s[8:9]
	s_nop 0
	v_cndmask_b32_e32 v101, 0, v99, vcc
	v_cndmask_b32_e64 v107, v99, v101, s[8:9]
	v_pk_fma_f32 v[100:101], v[108:109], s[96:97], v[162:163] op_sel_hi:[1,0,0]
	v_cmp_lt_f32_e32 vcc, s33, v108
	v_exp_f32_e32 v99, v100
	v_exp_f32_e32 v100, v101
	v_cvt_pk_bf16_f32 v98, v106, v107
	v_cndmask_b32_e32 v101, 0, v99, vcc
	v_cmp_lt_f32_e32 vcc, s33, v109
	v_cndmask_b32_e64 v108, v99, v101, s[8:9]
	s_nop 0
	v_cndmask_b32_e32 v102, 0, v100, vcc
	v_cndmask_b32_e64 v109, v100, v102, s[8:9]
	v_pk_fma_f32 v[100:101], v[110:111], s[96:97], v[162:163] op_sel_hi:[1,0,0]
	v_cmp_lt_f32_e32 vcc, s33, v110
	v_exp_f32_e32 v100, v100
	v_exp_f32_e32 v101, v101
	v_cvt_pk_bf16_f32 v99, v108, v109
	v_cndmask_b32_e32 v102, 0, v100, vcc
	v_cmp_lt_f32_e32 vcc, s33, v111
	v_cndmask_b32_e64 v110, v100, v102, s[8:9]
	s_nop 0
	v_cndmask_b32_e32 v103, 0, v101, vcc
	v_cndmask_b32_e64 v111, v101, v103, s[8:9]
	v_pk_fma_f32 v[102:103], v[112:113], s[96:97], v[162:163] op_sel_hi:[1,0,0]
	v_cmp_lt_f32_e32 vcc, s33, v112
	v_exp_f32_e32 v101, v102
	v_exp_f32_e32 v102, v103
	v_cvt_pk_bf16_f32 v100, v110, v111
	v_cndmask_b32_e32 v103, 0, v101, vcc
	v_cmp_lt_f32_e32 vcc, s33, v113
	v_cndmask_b32_e64 v112, v101, v103, s[8:9]
	s_nop 0
	v_cndmask_b32_e32 v104, 0, v102, vcc
	v_cndmask_b32_e64 v113, v102, v104, s[8:9]
	s_nop 0
	v_cvt_pk_bf16_f32 v101, v112, v113
	s_waitcnt lgkmcnt(0)
	s_nop 0
	v_mfma_f32_32x32x16_bf16 v[82:97], v[240:243], v[98:101], v[82:97]
	s_nop 0
	s_waitcnt lgkmcnt(0)
	v_mfma_f32_32x32x16_bf16 v[66:81], v[244:247], v[98:101], v[66:81]
	v_add_f32_e64 v98, v106, v116
	v_add_f32_e64 v99, v107, v117
	v_add_f32_e64 v98, v108, v98
	v_add_f32_e64 v99, v109, v99
	v_add_f32_e64 v98, v110, v98
	v_add_f32_e64 v99, v111, v99
	v_pk_add_f32 v[98:99], v[112:113], v[98:99]
	s_nop 0
	v_add_f32_e32 v98, v98, v99
	ds_bpermute_b32 v99, v165, v98
	s_cmp_gt_u32 s19, 5
	s_cbranch_scc1 .Ldma_m_win1
	s_add_i32 s98, s0, 0xffffb800
	s_cmp_lg_u32 s21, 0
	s_cselect_b32 s98, s98, 0xd800
	v_readfirstlane_b32 s99, v170
	s_add_i32 m0, s99, s98
	v_readfirstlane_b32 s99, v169
	global_load_lds_dwordx4 v[160:161], off
	s_add_i32 m0, s99, s98
	v_readfirstlane_b32 s99, v171
	global_load_lds_dwordx4 v[158:159], off
	s_add_i32 m0, s99, s98
	s_nop 0
	global_load_lds_dwordx4 v[156:157], off

; #define MFMA(a, b, c) __builtin_amdgcn_mfma_f32_32x32x16_bf16((a), (b), (c), 0, 0, 0)
; template <int N> DI void wait_vmcnt() { asm volatile("s_waitcnt vmcnt(%0)" ::"n"(N) : "memory"); }
;     ...
;   float mc = m * c2;
;   if (MODE == 2) mc = selbit ? mc : 1e30f;
;   const f32x2v c2v = {c2, c2}, mcv = {-mc, -mc};
;   f32x2v rs2 = {0.f, 0.f};
; #pragma unroll
;   for (int ks = 0; ks < 2; ++ks)
; #pragma unroll
;     for (int st = 0; st < 2; ++st) {
;       union { unsigned u[4]; bf16x8 v; } pf;
; #pragma unroll
;       for (int j = 0; j < 4; ++j) {
;         const int i0 = 8 * st + 2 * j;
;         f32x2v t = {S[ks][i0], S[ks][i0 + 1]};
;         t = __builtin_elementwise_fma(t, c2v, mcv);
;         f32x2v pv;
;         if (variant == 1) { pv = t; } else {
;         pv.x = __builtin_amdgcn_exp2f(t.x);
;         pv.y = __builtin_amdgcn_exp2f(t.y);
;         }
;         if (MODE != 0) {
;           if (need_mask) {
;             pv.x = (S[ks][i0] > -1e29f) ? pv.x : 0.f;
;             pv.y = (S[ks][i0 + 1] > -1e29f) ? pv.y : 0.f;
;           }
;         }
;         rs2 += pv;
;         pf.u[j] = __builtin_bit_cast(unsigned, __builtin_convertvector(pv, hwbf16x2));
;       }
; #pragma unroll
;       for (int d = 0; d < DV / 32; ++d) {
;         const char* vp = base + C::KBYTES + (d * 32 + lr) * C::VSTR + (ks * 32 + 16 * st + 4 * lh) * 2;
;         const s16x4 lo = *(const s16x4*)vp, hi = *(const s16x4*)(vp + 16);
;         const bf16x8 vf = __builtin_shufflevector(lo, hi, 0, 1, 2, 3, 4, 5, 6, 7);
;         O[d] = MFMA(vf, pf.v, O[d]);
;       }
;     }
;   float rs = rs2.x + rs2.y;
;   rs += __shfl_xor(rs, 32);
;     ...
;   asm volatile("s_waitcnt vmcnt(0)" ::: "memory");
; #pragma unroll
;   for (int t = 0; t < NST - 1; ++t)
;     if (t < ntile) FA_ISSUE(t, t)
;   int stage = 0;
;   for (int t = 0; t < ntile; ++t) {
;     int ahead = ((ntile < t + NST - 1) ? ntile : t + NST - 1) - (t + 1);
;     if (NST == 4 && ahead >= 2) wait_vmcnt<2 * NI>();
;     else if (ahead >= 1) wait_vmcnt<NI>();
;     else wait_vmcnt<0>();
;     raw_barrier();
;     if (t + NST - 1 < ntile) {
;       const int sn = (stage == 0) ? NST - 1 : stage - 1;
;       FA_ISSUE(t + NST - 1, sn)
.Lfast_win1:
	v_mul_f32_e32 v162, 0xbe38aa3b, v162
	v_pk_fma_f32 v[180:181], v[114:115], s[96:97], v[162:163] op_sel_hi:[1,0,0]
	v_exp_f32_e32 v188, v180
	v_exp_f32_e32 v189, v181
	v_pk_fma_f32 v[114:115], v[116:117], s[96:97], v[162:163] op_sel_hi:[1,0,0]
	v_exp_f32_e32 v190, v114
	v_exp_f32_e32 v191, v115
	v_cvt_pk_bf16_f32 v180, v188, v189
	v_pk_fma_f32 v[114:115], v[118:119], s[96:97], v[162:163] op_sel_hi:[1,0,0]
	v_exp_f32_e32 v192, v114
	v_exp_f32_e32 v193, v115
	v_cvt_pk_bf16_f32 v181, v190, v191
	v_pk_fma_f32 v[114:115], v[120:121], s[96:97], v[162:163] op_sel_hi:[1,0,0]
	v_exp_f32_e32 v120, v114
	v_exp_f32_e32 v121, v115
	v_cvt_pk_bf16_f32 v182, v192, v193
	v_cvt_pk_bf16_f32 v183, v120, v121
	s_waitcnt lgkmcnt(0)
	s_nop 0
	v_mfma_f32_32x32x16_bf16 v[82:97], v[216:219], v[180:183], v[82:97]
	s_waitcnt lgkmcnt(0)
	v_mfma_f32_32x32x16_bf16 v[66:81], v[220:223], v[180:183], v[66:81]
	v_add_f32_e64 v116, v188, 0
	v_add_f32_e64 v117, v189, 0
	v_add_f32_e64 v116, v190, v116
	v_add_f32_e64 v117, v191, v117
	v_add_f32_e64 v116, v192, v116
	v_add_f32_e64 v117, v193, v117
	v_pk_add_f32 v[180:181], v[120:121], v[116:117]
	v_pk_fma_f32 v[116:117], v[122:123], s[96:97], v[162:163] op_sel_hi:[1,0,0]
	v_exp_f32_e32 v182, v116
	v_exp_f32_e32 v183, v117
	v_pk_fma_f32 v[118:119], v[124:125], s[96:97], v[162:163] op_sel_hi:[1,0,0]
	v_exp_f32_e32 v124, v118
	v_exp_f32_e32 v125, v119
	v_cvt_pk_bf16_f32 v116, v182, v183
	v_pk_fma_f32 v[118:119], v[126:127], s[96:97], v[162:163] op_sel_hi:[1,0,0]
	v_exp_f32_e32 v126, v118
	v_exp_f32_e32 v127, v119
	v_cvt_pk_bf16_f32 v117, v124, v125
	v_pk_fma_f32 v[120:121], v[128:129], s[96:97], v[162:163] op_sel_hi:[1,0,0]
	v_exp_f32_e32 v128, v120
	v_exp_f32_e32 v129, v121
	v_cvt_pk_bf16_f32 v118, v126, v127
	v_cvt_pk_bf16_f32 v119, v128, v129
	s_nop 1
	v_mfma_f32_32x32x16_bf16 v[82:97], v[224:227], v[116:119], v[82:97]
	s_waitcnt lgkmcnt(0)
	v_mfma_f32_32x32x16_bf16 v[66:81], v[228:231], v[116:119], v[66:81]
	v_fma_f32 v118, v98, s96, v162
	v_fma_f32 v119, v99, s96, v162
	v_fma_f32 v120, v100, s96, v162
	v_fma_f32 v121, v101, s96, v162
	v_exp_f32_e32 v118, v118
	v_exp_f32_e32 v119, v119
	v_pk_add_f32 v[116:117], v[182:183], v[180:181]
	v_pk_add_f32 v[116:117], v[124:125], v[116:117]
	v_exp_f32_e32 v120, v120
	v_exp_f32_e32 v121, v121
	v_cvt_pk_bf16_f32 v98, v118, v119
	v_pk_add_f32 v[116:117], v[126:127], v[116:117]
	v_pk_add_f32 v[116:117], v[128:129], v[116:117]
	v_pk_fma_f32 v[100:101], v[102:103], s[96:97], v[162:163] op_sel_hi:[1,0,0]
	v_exp_f32_e32 v122, v100
	v_exp_f32_e32 v123, v101
	v_cvt_pk_bf16_f32 v99, v120, v121
	v_pk_fma_f32 v[102:103], v[104:105], s[96:97], v[162:163] op_sel_hi:[1,0,0]
	v_exp_f32_e32 v124, v102
	v_exp_f32_e32 v125, v103
	v_cvt_pk_bf16_f32 v100, v122, v123
	v_cvt_pk_bf16_f32 v101, v124, v125
	s_waitcnt lgkmcnt(0)
	s_nop 0
	v_mfma_f32_32x32x16_bf16 v[82:97], v[232:235], v[98:101], v[82:97]
	s_waitcnt lgkmcnt(0)
	v_mfma_f32_32x32x16_bf16 v[66:81], v[236:239], v[98:101], v[66:81]
	v_add_f32_e64 v98, v118, v116
	v_add_f32_e64 v99, v119, v117
	v_add_f32_e64 v98, v120, v98
	v_add_f32_e64 v99, v121, v99
	v_add_f32_e64 v98, v122, v98
	v_add_f32_e64 v99, v123, v99
	v_pk_add_f32 v[116:117], v[124:125], v[98:99]
	v_pk_fma_f32 v[98:99], v[106:107], s[96:97], v[162:163] op_sel_hi:[1,0,0]
	v_exp_f32_e32 v106, v98
	v_exp_f32_e32 v107, v99
	v_pk_fma_f32 v[100:101], v[108:109], s[96:97], v[162:163] op_sel_hi:[1,0,0]
	v_exp_f32_e32 v108, v100
	v_exp_f32_e32 v109, v101
	v_cvt_pk_bf16_f32 v98, v106, v107
	v_pk_fma_f32 v[100:101], v[110:111], s[96:97], v[162:163] op_sel_hi:[1,0,0]
	v_exp_f32_e32 v110, v100
	v_exp_f32_e32 v111, v101
	v_cvt_pk_bf16_f32 v99, v108, v109
	v_pk_fma_f32 v[102:103], v[112:113], s[96:97], v[162:163] op_sel_hi:[1,0,0]
	v_exp_f32_e32 v112, v102
	v_exp_f32_e32 v113, v103
	v_cvt_pk_bf16_f32 v100, v110, v111
	v_cvt_pk_bf16_f32 v101, v112, v113
	s_waitcnt lgkmcnt(0)
	s_nop 0
	v_mfma_f32_32x32x16_bf16 v[82:97], v[240:243], v[98:101], v[82:97]
	s_waitcnt lgkmcnt(0)
	v_mfma_f32_32x32x16_bf16 v[66:81], v[244:247], v[98:101], v[66:81]
	v_add_f32_e64 v98, v106, v116
	v_add_f32_e64 v99, v107, v117
	v_add_f32_e64 v98, v108, v98
	v_add_f32_e64 v99, v109, v99
	v_add_f32_e64 v98, v110, v98
	v_add_f32_e64 v99, v111, v99
	v_pk_add_f32 v[98:99], v[112:113], v[98:99]
	v_add_f32_e32 v98, v98, v99
	ds_bpermute_b32 v99, v165, v98
	s_cmp_gt_u32 s19, 5
	s_cbranch_scc1 .Ldma_f_win1
	s_add_i32 s98, s0, 0xffffb800
	s_cmp_lg_u32 s21, 0
	s_cselect_b32 s98, s98, 0xd800
	v_readfirstlane_b32 s99, v170
	s_add_i32 m0, s99, s98
	v_readfirstlane_b32 s99, v169
	global_load_lds_dwordx4 v[160:161], off
	s_add_i32 m0, s99, s98
	v_readfirstlane_b32 s99, v171
	global_load_lds_dwordx4 v[158:159], off
	s_add_i32 m0, s99, s98
	s_nop 0
	global_load_lds_dwordx4 v[156:157], off

; template <int N> DI void wait_vmcnt() { asm volatile("s_waitcnt vmcnt(%0)" ::"n"(N) : "memory"); }
;     ...
;   asm volatile("s_waitcnt vmcnt(0)" ::: "memory");
; #pragma unroll
;   for (int t = 0; t < NST - 1; ++t)
;     if (t < ntile) FA_ISSUE(t, t)
;   int stage = 0;
;   for (int t = 0; t < ntile; ++t) {
;     int ahead = ((ntile < t + NST - 1) ? ntile : t + NST - 1) - (t + 1);
;     if (NST == 4 && ahead >= 2) wait_vmcnt<2 * NI>();
;     else if (ahead >= 1) wait_vmcnt<NI>();
;     else wait_vmcnt<0>();
;     raw_barrier();
;     if (t + NST - 1 < ntile) {
;       const int sn = (stage == 0) ? NST - 1 : stage - 1;
;       FA_ISSUE(t + NST - 1, sn)
;     }
.LBB0_456:
	s_cmp_gt_u32 s19, 5
	s_cbranch_scc1 .Ldma_skip_win1
	s_add_i32 s98, s0, 0xffffb800
	s_cmp_lg_u32 s21, 0
	s_cselect_b32 s98, s98, 0xd800
	v_readfirstlane_b32 s99, v170
	s_add_i32 m0, s99, s98
	v_readfirstlane_b32 s99, v169
	global_load_lds_dwordx4 v[160:161], off
	s_add_i32 m0, s99, s98
	v_readfirstlane_b32 s99, v171
	global_load_lds_dwordx4 v[158:159], off
	s_add_i32 m0, s99, s98
	s_nop 0
	global_load_lds_dwordx4 v[156:157], off

; #define MFMA(a, b, c) __builtin_amdgcn_mfma_f32_32x32x16_bf16((a), (b), (c), 0, 0, 0)
;     ...
;   float mc = m * c2;
;   if (MODE == 2) mc = selbit ? mc : 1e30f;
;   const f32x2v c2v = {c2, c2}, mcv = {-mc, -mc};
;   f32x2v rs2 = {0.f, 0.f};
; #pragma unroll
;   for (int ks = 0; ks < 2; ++ks)
; #pragma unroll
;     for (int st = 0; st < 2; ++st) {
;       union { unsigned u[4]; bf16x8 v; } pf;
; #pragma unroll
;       for (int j = 0; j < 4; ++j) {
;         const int i0 = 8 * st + 2 * j;
;         f32x2v t = {S[ks][i0], S[ks][i0 + 1]};
;         t = __builtin_elementwise_fma(t, c2v, mcv);
;         f32x2v pv;
;         if (variant == 1) { pv = t; } else {
;         pv.x = __builtin_amdgcn_exp2f(t.x);
;         pv.y = __builtin_amdgcn_exp2f(t.y);
;         }
;         if (MODE != 0) {
;           if (need_mask) {
;             pv.x = (S[ks][i0] > -1e29f) ? pv.x : 0.f;
;             pv.y = (S[ks][i0 + 1] > -1e29f) ? pv.y : 0.f;
;           }
;         }
;         rs2 += pv;
;         pf.u[j] = __builtin_bit_cast(unsigned, __builtin_convertvector(pv, hwbf16x2));
;       }
; #pragma unroll
;       for (int d = 0; d < DV / 32; ++d) {
;         const char* vp = base + C::KBYTES + (d * 32 + lr) * C::VSTR + (ks * 32 + 16 * st + 4 * lh) * 2;
;         const s16x4 lo = *(const s16x4*)vp, hi = *(const s16x4*)(vp + 16);
;         const bf16x8 vf = __builtin_shufflevector(lo, hi, 0, 1, 2, 3, 4, 5, 6, 7);
;         O[d] = MFMA(vf, pf.v, O[d]);
;       }
;     }
.LBB0_487:
	s_cmp_eq_u64 s[8:9], 0
	s_cbranch_scc1 .Lfast_mla2
	v_mul_f32_e32 v104, 0xbe16c740, v104
	s_mov_b32 s12, 0x3e16c740
	v_pk_fma_f32 v[118:119], v[50:51], s[12:13], v[104:105] op_sel_hi:[1,0,0]
	v_cmp_lt_f32_e32 vcc, s33, v50
	v_exp_f32_e32 v117, v118
	v_exp_f32_e32 v118, v119
	v_cndmask_b32_e32 v50, 0, v117, vcc
	v_cmp_lt_f32_e32 vcc, s33, v51
	v_cndmask_b32_e64 v126, v117, v50, s[8:9]
	s_nop 0
	v_cndmask_b32_e32 v51, 0, v118, vcc
	v_cndmask_b32_e64 v127, v118, v51, s[8:9]
	v_pk_fma_f32 v[50:51], v[52:53], s[12:13], v[104:105] op_sel_hi:[1,0,0]
	v_cmp_lt_f32_e32 vcc, s33, v52
	v_exp_f32_e32 v50, v50
	v_exp_f32_e32 v51, v51
	v_cvt_pk_bf16_f32 v118, v126, v127
	v_cndmask_b32_e32 v52, 0, v50, vcc
	v_cmp_lt_f32_e32 vcc, s33, v53
	v_cndmask_b32_e64 v128, v50, v52, s[8:9]
	s_nop 0
	v_cndmask_b32_e32 v53, 0, v51, vcc
	v_cndmask_b32_e64 v129, v51, v53, s[8:9]
	v_pk_fma_f32 v[50:51], v[54:55], s[12:13], v[104:105] op_sel_hi:[1,0,0]
	v_cmp_lt_f32_e32 vcc, s33, v54
	v_exp_f32_e32 v50, v50
	v_exp_f32_e32 v51, v51
	v_cvt_pk_bf16_f32 v119, v128, v129
	v_cndmask_b32_e32 v52, 0, v50, vcc
	v_cmp_lt_f32_e32 vcc, s33, v55
	v_cndmask_b32_e64 v130, v50, v52, s[8:9]
	s_nop 0
	v_cndmask_b32_e32 v53, 0, v51, vcc
	v_cndmask_b32_e64 v131, v51, v53, s[8:9]
	v_pk_fma_f32 v[50:51], v[56:57], s[12:13], v[104:105] op_sel_hi:[1,0,0]
	v_cmp_lt_f32_e32 vcc, s33, v56
	v_exp_f32_e32 v50, v50
	v_exp_f32_e32 v51, v51
	v_cvt_pk_bf16_f32 v120, v130, v131
	v_cndmask_b32_e32 v52, 0, v50, vcc
	v_cmp_lt_f32_e32 vcc, s33, v57
	v_cndmask_b32_e64 v56, v50, v52, s[8:9]
	s_nop 0
	v_cndmask_b32_e32 v53, 0, v51, vcc
	v_cndmask_b32_e64 v57, v51, v53, s[8:9]
	v_cvt_pk_bf16_f32 v121, v56, v57
	v_cmp_lt_f32_e32 vcc, s33, v58
	s_waitcnt lgkmcnt(0)
	v_mfma_f32_32x32x16_bf16 v[18:33], v[216:219], v[118:121], v[18:33]
	s_waitcnt lgkmcnt(0)
	v_mfma_f32_32x32x16_bf16 v[2:17], v[220:223], v[118:121], v[2:17]
	v_add_f32_e64 v52, v126, 0
	v_add_f32_e64 v53, v127, 0
	v_add_f32_e64 v52, v128, v52
	v_add_f32_e64 v53, v129, v53
	v_add_f32_e64 v52, v130, v52
	v_add_f32_e64 v53, v131, v53
	v_pk_add_f32 v[118:119], v[56:57], v[52:53]
	v_pk_fma_f32 v[52:53], v[58:59], s[12:13], v[104:105] op_sel_hi:[1,0,0]
	s_nop 0
	v_exp_f32_e32 v52, v52
	v_exp_f32_e32 v53, v53
	v_cndmask_b32_e32 v54, 0, v52, vcc
	v_cmp_lt_f32_e32 vcc, s33, v59
	v_cndmask_b32_e64 v120, v52, v54, s[8:9]
	s_nop 0
	v_cndmask_b32_e32 v55, 0, v53, vcc
	v_cndmask_b32_e64 v121, v53, v55, s[8:9]
	v_pk_fma_f32 v[54:55], v[60:61], s[12:13], v[104:105] op_sel_hi:[1,0,0]
	v_cmp_lt_f32_e32 vcc, s33, v60
	v_exp_f32_e32 v53, v54
	v_exp_f32_e32 v54, v55
	v_cvt_pk_bf16_f32 v52, v120, v121
	v_cndmask_b32_e32 v55, 0, v53, vcc
	v_cmp_lt_f32_e32 vcc, s33, v61
	v_cndmask_b32_e64 v60, v53, v55, s[8:9]
	s_nop 0
	v_cndmask_b32_e32 v56, 0, v54, vcc
	v_cndmask_b32_e64 v61, v54, v56, s[8:9]
	v_pk_fma_f32 v[54:55], v[62:63], s[12:13], v[104:105] op_sel_hi:[1,0,0]
	v_cmp_lt_f32_e32 vcc, s33, v62
	v_exp_f32_e32 v54, v54
	v_exp_f32_e32 v55, v55
	v_cvt_pk_bf16_f32 v53, v60, v61
	v_cndmask_b32_e32 v56, 0, v54, vcc
	v_cmp_lt_f32_e32 vcc, s33, v63
	v_cndmask_b32_e64 v62, v54, v56, s[8:9]
	s_nop 0
	v_cndmask_b32_e32 v57, 0, v55, vcc
	v_cndmask_b32_e64 v63, v55, v57, s[8:9]
	v_pk_fma_f32 v[56:57], v[64:65], s[12:13], v[104:105] op_sel_hi:[1,0,0]
	v_cmp_lt_f32_e32 vcc, s33, v64
	v_exp_f32_e32 v55, v56
	v_exp_f32_e32 v56, v57
	v_cvt_pk_bf16_f32 v54, v62, v63
	v_cndmask_b32_e32 v57, 0, v55, vcc
	v_cmp_lt_f32_e32 vcc, s33, v65
	v_cndmask_b32_e64 v64, v55, v57, s[8:9]
	s_nop 0
	v_cndmask_b32_e32 v58, 0, v56, vcc
	v_cndmask_b32_e64 v65, v56, v58, s[8:9]
	v_cvt_pk_bf16_f32 v55, v64, v65
	v_cmp_lt_f32_e32 vcc, s33, v34
	s_nop 0
	v_mfma_f32_32x32x16_bf16 v[18:33], v[224:227], v[52:55], v[18:33]
	s_waitcnt lgkmcnt(0)
; #define MFMA(a, b, c) __builtin_amdgcn_mfma_f32_32x32x16_bf16((a), (b), (c), 0, 0, 0)
; template <int N> DI void wait_vmcnt() { asm volatile("s_waitcnt vmcnt(%0)" ::"n"(N) : "memory"); }
;     ...
; #pragma unroll
;       for (int j = 0; j < 4; ++j) {
;         const int i0 = 8 * st + 2 * j;
;         f32x2v t = {S[ks][i0], S[ks][i0 + 1]};
;         t = __builtin_elementwise_fma(t, c2v, mcv);
;         f32x2v pv;
;         if (variant == 1) { pv = t; } else {
;         pv.x = __builtin_amdgcn_exp2f(t.x);
;         pv.y = __builtin_amdgcn_exp2f(t.y);
;         }
;         if (MODE != 0) {
;           if (need_mask) {
;             pv.x = (S[ks][i0] > -1e29f) ? pv.x : 0.f;
;             pv.y = (S[ks][i0 + 1] > -1e29f) ? pv.y : 0.f;
;           }
;         }
;         rs2 += pv;
;         pf.u[j] = __builtin_bit_cast(unsigned, __builtin_convertvector(pv, hwbf16x2));
;       }
; #pragma unroll
;       for (int d = 0; d < DV / 32; ++d) {
;         const char* vp = base + C::KBYTES + (d * 32 + lr) * C::VSTR + (ks * 32 + 16 * st + 4 * lh) * 2;
;         const s16x4 lo = *(const s16x4*)vp, hi = *(const s16x4*)(vp + 16);
;         const bf16x8 vf = __builtin_shufflevector(lo, hi, 0, 1, 2, 3, 4, 5, 6, 7);
;         O[d] = MFMA(vf, pf.v, O[d]);
;       }
;     }
;   float rs = rs2.x + rs2.y;
;   rs += __shfl_xor(rs, 32);
;     ...
;   asm volatile("s_waitcnt vmcnt(0)" ::: "memory");
; #pragma unroll
;   for (int t = 0; t < NST - 1; ++t)
;     if (t < ntile) FA_ISSUE(t, t)
;   int stage = 0;
;   for (int t = 0; t < ntile; ++t) {
;     int ahead = ((ntile < t + NST - 1) ? ntile : t + NST - 1) - (t + 1);
;     if (NST == 4 && ahead >= 2) wait_vmcnt<2 * NI>();
;     else if (ahead >= 1) wait_vmcnt<NI>();
;     else wait_vmcnt<0>();
;     raw_barrier();
;     if (t + NST - 1 < ntile) {
;       const int sn = (stage == 0) ? NST - 1 : stage - 1;
;       FA_ISSUE(t + NST - 1, sn)
	v_mfma_f32_32x32x16_bf16 v[2:17], v[228:231], v[52:55], v[2:17]
	v_fma_f32 v54, v34, s12, v104
	v_fma_f32 v55, v35, s12, v104
	v_fma_f32 v56, v36, s12, v104
	v_fma_f32 v57, v37, s12, v104
	v_exp_f32_e32 v54, v54
	v_exp_f32_e32 v55, v55
	v_pk_add_f32 v[52:53], v[120:121], v[118:119]
	v_cndmask_b32_e32 v34, 0, v54, vcc
	v_cmp_lt_f32_e32 vcc, s33, v35
	v_pk_add_f32 v[52:53], v[60:61], v[52:53]
	v_cndmask_b32_e64 v54, v54, v34, s[8:9]
	v_cndmask_b32_e32 v35, 0, v55, vcc
	v_cndmask_b32_e64 v55, v55, v35, s[8:9]
	v_exp_f32_e32 v35, v56
	v_exp_f32_e32 v56, v57
	v_cmp_lt_f32_e32 vcc, s33, v36
	v_cvt_pk_bf16_f32 v34, v54, v55
	v_pk_add_f32 v[52:53], v[62:63], v[52:53]
	v_cndmask_b32_e32 v36, 0, v35, vcc
	v_cmp_lt_f32_e32 vcc, s33, v37
	v_pk_add_f32 v[52:53], v[64:65], v[52:53]
	s_nop 0
	v_cndmask_b32_e32 v37, 0, v56, vcc
	v_cndmask_b32_e64 v57, v56, v37, s[8:9]
	v_cndmask_b32_e64 v56, v35, v36, s[8:9]
	v_pk_fma_f32 v[36:37], v[38:39], s[12:13], v[104:105] op_sel_hi:[1,0,0]
	v_cmp_lt_f32_e32 vcc, s33, v38
	v_exp_f32_e32 v36, v36
	v_exp_f32_e32 v37, v37
	v_cvt_pk_bf16_f32 v35, v56, v57
	v_cndmask_b32_e32 v38, 0, v36, vcc
	v_cmp_lt_f32_e32 vcc, s33, v39
	v_cndmask_b32_e64 v58, v36, v38, s[8:9]
	s_nop 0
	v_cndmask_b32_e32 v39, 0, v37, vcc
	v_cndmask_b32_e64 v59, v37, v39, s[8:9]
	v_pk_fma_f32 v[38:39], v[40:41], s[12:13], v[104:105] op_sel_hi:[1,0,0]
	v_cmp_lt_f32_e32 vcc, s33, v40
	v_exp_f32_e32 v37, v38
	v_exp_f32_e32 v38, v39
	v_cvt_pk_bf16_f32 v36, v58, v59
	v_cndmask_b32_e32 v39, 0, v37, vcc
	v_cmp_lt_f32_e32 vcc, s33, v41
	v_cndmask_b32_e64 v60, v37, v39, s[8:9]
	s_nop 0
	v_cndmask_b32_e32 v40, 0, v38, vcc
	v_cndmask_b32_e64 v61, v38, v40, s[8:9]
	v_cvt_pk_bf16_f32 v37, v60, v61
	v_cmp_lt_f32_e32 vcc, s33, v42
	s_waitcnt lgkmcnt(0)
	v_mfma_f32_32x32x16_bf16 v[18:33], v[232:235], v[34:37], v[18:33]
	s_waitcnt lgkmcnt(0)
	v_mfma_f32_32x32x16_bf16 v[2:17], v[236:239], v[34:37], v[2:17]
	v_add_f32_e64 v34, v54, v52
	v_add_f32_e64 v35, v55, v53
	v_add_f32_e64 v34, v56, v34
	v_add_f32_e64 v35, v57, v35
	v_add_f32_e64 v34, v58, v34
	v_add_f32_e64 v35, v59, v35
	v_pk_add_f32 v[52:53], v[60:61], v[34:35]
	v_pk_fma_f32 v[34:35], v[42:43], s[12:13], v[104:105] op_sel_hi:[1,0,0]
	s_nop 0
	v_exp_f32_e32 v34, v34
	v_exp_f32_e32 v35, v35
	v_cndmask_b32_e32 v36, 0, v34, vcc
	v_cmp_lt_f32_e32 vcc, s33, v43
	v_cndmask_b32_e64 v42, v34, v36, s[8:9]
	s_nop 0
	v_cndmask_b32_e32 v37, 0, v35, vcc
	v_cndmask_b32_e64 v43, v35, v37, s[8:9]
	v_pk_fma_f32 v[36:37], v[44:45], s[12:13], v[104:105] op_sel_hi:[1,0,0]
	v_cmp_lt_f32_e32 vcc, s33, v44
	v_exp_f32_e32 v35, v36
	v_exp_f32_e32 v36, v37
	v_cvt_pk_bf16_f32 v34, v42, v43
	v_cndmask_b32_e32 v37, 0, v35, vcc
	v_cmp_lt_f32_e32 vcc, s33, v45
	v_cndmask_b32_e64 v44, v35, v37, s[8:9]
	s_nop 0
	v_cndmask_b32_e32 v38, 0, v36, vcc
	v_cndmask_b32_e64 v45, v36, v38, s[8:9]
	v_pk_fma_f32 v[36:37], v[46:47], s[12:13], v[104:105] op_sel_hi:[1,0,0]
	v_cmp_lt_f32_e32 vcc, s33, v46
	v_exp_f32_e32 v36, v36
	v_exp_f32_e32 v37, v37
	v_cvt_pk_bf16_f32 v35, v44, v45
	v_cndmask_b32_e32 v38, 0, v36, vcc
	v_cmp_lt_f32_e32 vcc, s33, v47
	v_cndmask_b32_e64 v46, v36, v38, s[8:9]
	s_nop 0
	v_cndmask_b32_e32 v39, 0, v37, vcc
	v_cndmask_b32_e64 v47, v37, v39, s[8:9]
	v_pk_fma_f32 v[38:39], v[48:49], s[12:13], v[104:105] op_sel_hi:[1,0,0]
	v_cmp_lt_f32_e32 vcc, s33, v48
	v_exp_f32_e32 v37, v38
	v_exp_f32_e32 v38, v39
	v_cvt_pk_bf16_f32 v36, v46, v47
	v_cndmask_b32_e32 v39, 0, v37, vcc
	v_cmp_lt_f32_e32 vcc, s33, v49
	v_cndmask_b32_e64 v48, v37, v39, s[8:9]
	s_nop 0
	v_cndmask_b32_e32 v40, 0, v38, vcc
	v_cndmask_b32_e64 v49, v38, v40, s[8:9]
	v_cvt_pk_bf16_f32 v37, v48, v49
	s_waitcnt lgkmcnt(0)
	s_nop 0
	v_mfma_f32_32x32x16_bf16 v[18:33], v[240:243], v[34:37], v[18:33]
	s_waitcnt lgkmcnt(0)
	v_mfma_f32_32x32x16_bf16 v[2:17], v[244:247], v[34:37], v[2:17]
	v_add_f32_e64 v34, v42, v52
	v_add_f32_e64 v35, v43, v53
	v_add_f32_e64 v34, v44, v34
	v_add_f32_e64 v35, v45, v35
	v_add_f32_e64 v34, v46, v34
	v_add_f32_e64 v35, v47, v35
	v_pk_add_f32 v[34:35], v[48:49], v[34:35]
	s_nop 0
	v_add_f32_e32 v34, v34, v35
	ds_bpermute_b32 v35, v165, v34
	s_cmp_ge_u32 s17, s18
	s_cbranch_scc1 .Ldma_m_mla2
	s_add_i32 s98, s6, 0xffffa800
	s_cmp_lg_u32 s44, 0
	s_cselect_b32 s98, s98, 0x10800
	v_readfirstlane_b32 s99, v107
	s_add_i32 m0, s99, s98
	v_readfirstlane_b32 s99, v93
	global_load_lds_dwordx4 v[102:103], off
	s_add_i32 m0, s99, s98
	v_readfirstlane_b32 s99, v108
	global_load_lds_dwordx4 v[100:101], off
	s_add_i32 m0, s99, s98
	s_nop 0
	global_load_lds_dwordx4 v[98:99], off

; #define MFMA(a, b, c) __builtin_amdgcn_mfma_f32_32x32x16_bf16((a), (b), (c), 0, 0, 0)
; template <int N> DI void wait_vmcnt() { asm volatile("s_waitcnt vmcnt(%0)" ::"n"(N) : "memory"); }
;     ...
;   float mc = m * c2;
;   if (MODE == 2) mc = selbit ? mc : 1e30f;
;   const f32x2v c2v = {c2, c2}, mcv = {-mc, -mc};
;   f32x2v rs2 = {0.f, 0.f};
; #pragma unroll
;   for (int ks = 0; ks < 2; ++ks)
; #pragma unroll
;     for (int st = 0; st < 2; ++st) {
;       union { unsigned u[4]; bf16x8 v; } pf;
; #pragma unroll
;       for (int j = 0; j < 4; ++j) {
;         const int i0 = 8 * st + 2 * j;
;         f32x2v t = {S[ks][i0], S[ks][i0 + 1]};
;         t = __builtin_elementwise_fma(t, c2v, mcv);
;         f32x2v pv;
;         if (variant == 1) { pv = t; } else {
;         pv.x = __builtin_amdgcn_exp2f(t.x);
;         pv.y = __builtin_amdgcn_exp2f(t.y);
;         }
;         if (MODE != 0) {
;           if (need_mask) {
;             pv.x = (S[ks][i0] > -1e29f) ? pv.x : 0.f;
;             pv.y = (S[ks][i0 + 1] > -1e29f) ? pv.y : 0.f;
;           }
;         }
;         rs2 += pv;
;         pf.u[j] = __builtin_bit_cast(unsigned, __builtin_convertvector(pv, hwbf16x2));
;       }
; #pragma unroll
;       for (int d = 0; d < DV / 32; ++d) {
;         const char* vp = base + C::KBYTES + (d * 32 + lr) * C::VSTR + (ks * 32 + 16 * st + 4 * lh) * 2;
;         const s16x4 lo = *(const s16x4*)vp, hi = *(const s16x4*)(vp + 16);
;         const bf16x8 vf = __builtin_shufflevector(lo, hi, 0, 1, 2, 3, 4, 5, 6, 7);
;         O[d] = MFMA(vf, pf.v, O[d]);
;       }
;     }
;   float rs = rs2.x + rs2.y;
;   rs += __shfl_xor(rs, 32);
;     ...
;   asm volatile("s_waitcnt vmcnt(0)" ::: "memory");
; #pragma unroll
;   for (int t = 0; t < NST - 1; ++t)
;     if (t < ntile) FA_ISSUE(t, t)
;   int stage = 0;
;   for (int t = 0; t < ntile; ++t) {
;     int ahead = ((ntile < t + NST - 1) ? ntile : t + NST - 1) - (t + 1);
;     if (NST == 4 && ahead >= 2) wait_vmcnt<2 * NI>();
;     else if (ahead >= 1) wait_vmcnt<NI>();
;     else wait_vmcnt<0>();
;     raw_barrier();
;     if (t + NST - 1 < ntile) {
;       const int sn = (stage == 0) ? NST - 1 : stage - 1;
;       FA_ISSUE(t + NST - 1, sn)
.Lfast_mla2:
	v_mul_f32_e32 v104, 0xbe16c740, v104
	s_mov_b32 s12, 0x3e16c740
	v_pk_fma_f32 v[118:119], v[50:51], s[12:13], v[104:105] op_sel_hi:[1,0,0]
	v_exp_f32_e32 v126, v118
	v_exp_f32_e32 v127, v119
	v_pk_fma_f32 v[50:51], v[52:53], s[12:13], v[104:105] op_sel_hi:[1,0,0]
	v_exp_f32_e32 v128, v50
	v_exp_f32_e32 v129, v51
	v_cvt_pk_bf16_f32 v118, v126, v127
	v_pk_fma_f32 v[50:51], v[54:55], s[12:13], v[104:105] op_sel_hi:[1,0,0]
	v_exp_f32_e32 v130, v50
	v_exp_f32_e32 v131, v51
	v_cvt_pk_bf16_f32 v119, v128, v129
	v_pk_fma_f32 v[50:51], v[56:57], s[12:13], v[104:105] op_sel_hi:[1,0,0]
	v_exp_f32_e32 v56, v50
	v_exp_f32_e32 v57, v51
	v_cvt_pk_bf16_f32 v120, v130, v131
	v_cvt_pk_bf16_f32 v121, v56, v57
	s_waitcnt lgkmcnt(0)
	s_nop 0
	v_mfma_f32_32x32x16_bf16 v[18:33], v[216:219], v[118:121], v[18:33]
	s_waitcnt lgkmcnt(0)
	v_mfma_f32_32x32x16_bf16 v[2:17], v[220:223], v[118:121], v[2:17]
	v_add_f32_e64 v52, v126, 0
	v_add_f32_e64 v53, v127, 0
	v_add_f32_e64 v52, v128, v52
	v_add_f32_e64 v53, v129, v53
	v_add_f32_e64 v52, v130, v52
	v_add_f32_e64 v53, v131, v53
	v_pk_add_f32 v[118:119], v[56:57], v[52:53]
	v_pk_fma_f32 v[52:53], v[58:59], s[12:13], v[104:105] op_sel_hi:[1,0,0]
	v_exp_f32_e32 v120, v52
	v_exp_f32_e32 v121, v53
	v_pk_fma_f32 v[54:55], v[60:61], s[12:13], v[104:105] op_sel_hi:[1,0,0]
	v_exp_f32_e32 v60, v54
	v_exp_f32_e32 v61, v55
	v_cvt_pk_bf16_f32 v52, v120, v121
	v_pk_fma_f32 v[54:55], v[62:63], s[12:13], v[104:105] op_sel_hi:[1,0,0]
	v_exp_f32_e32 v62, v54
	v_exp_f32_e32 v63, v55
	v_cvt_pk_bf16_f32 v53, v60, v61
	v_pk_fma_f32 v[56:57], v[64:65], s[12:13], v[104:105] op_sel_hi:[1,0,0]
	v_exp_f32_e32 v64, v56
	v_exp_f32_e32 v65, v57
	v_cvt_pk_bf16_f32 v54, v62, v63
	v_cvt_pk_bf16_f32 v55, v64, v65
	s_nop 1
	v_mfma_f32_32x32x16_bf16 v[18:33], v[224:227], v[52:55], v[18:33]
	s_waitcnt lgkmcnt(0)
	v_mfma_f32_32x32x16_bf16 v[2:17], v[228:231], v[52:55], v[2:17]
	v_fma_f32 v54, v34, s12, v104
	v_fma_f32 v55, v35, s12, v104
	v_fma_f32 v56, v36, s12, v104
	v_fma_f32 v57, v37, s12, v104
	v_exp_f32_e32 v54, v54
	v_exp_f32_e32 v55, v55
	v_pk_add_f32 v[52:53], v[120:121], v[118:119]
	v_pk_add_f32 v[52:53], v[60:61], v[52:53]
	v_exp_f32_e32 v56, v56
	v_exp_f32_e32 v57, v57
	v_cvt_pk_bf16_f32 v34, v54, v55
	v_pk_add_f32 v[52:53], v[62:63], v[52:53]
	v_pk_add_f32 v[52:53], v[64:65], v[52:53]
	v_pk_fma_f32 v[36:37], v[38:39], s[12:13], v[104:105] op_sel_hi:[1,0,0]
	v_exp_f32_e32 v58, v36
	v_exp_f32_e32 v59, v37
	v_cvt_pk_bf16_f32 v35, v56, v57
	v_pk_fma_f32 v[38:39], v[40:41], s[12:13], v[104:105] op_sel_hi:[1,0,0]
	v_exp_f32_e32 v60, v38
	v_exp_f32_e32 v61, v39
	v_cvt_pk_bf16_f32 v36, v58, v59
	v_cvt_pk_bf16_f32 v37, v60, v61
	s_waitcnt lgkmcnt(0)
	s_nop 0
	v_mfma_f32_32x32x16_bf16 v[18:33], v[232:235], v[34:37], v[18:33]
	s_waitcnt lgkmcnt(0)
	v_mfma_f32_32x32x16_bf16 v[2:17], v[236:239], v[34:37], v[2:17]
	v_add_f32_e64 v34, v54, v52
	v_add_f32_e64 v35, v55, v53
	v_add_f32_e64 v34, v56, v34
	v_add_f32_e64 v35, v57, v35
	v_add_f32_e64 v34, v58, v34
	v_add_f32_e64 v35, v59, v35
	v_pk_add_f32 v[52:53], v[60:61], v[34:35]
	v_pk_fma_f32 v[34:35], v[42:43], s[12:13], v[104:105] op_sel_hi:[1,0,0]
	v_exp_f32_e32 v42, v34
	v_exp_f32_e32 v43, v35
	v_pk_fma_f32 v[36:37], v[44:45], s[12:13], v[104:105] op_sel_hi:[1,0,0]
	v_exp_f32_e32 v44, v36
	v_exp_f32_e32 v45, v37
	v_cvt_pk_bf16_f32 v34, v42, v43
	v_pk_fma_f32 v[36:37], v[46:47], s[12:13], v[104:105] op_sel_hi:[1,0,0]
	v_exp_f32_e32 v46, v36
	v_exp_f32_e32 v47, v37
	v_cvt_pk_bf16_f32 v35, v44, v45
	v_pk_fma_f32 v[38:39], v[48:49], s[12:13], v[104:105] op_sel_hi:[1,0,0]
	v_exp_f32_e32 v48, v38
	v_exp_f32_e32 v49, v39
	v_cvt_pk_bf16_f32 v36, v46, v47
	v_cvt_pk_bf16_f32 v37, v48, v49
	s_waitcnt lgkmcnt(0)
	s_nop 0
	v_mfma_f32_32x32x16_bf16 v[18:33], v[240:243], v[34:37], v[18:33]
	s_waitcnt lgkmcnt(0)
	v_mfma_f32_32x32x16_bf16 v[2:17], v[244:247], v[34:37], v[2:17]
	v_add_f32_e64 v34, v42, v52
	v_add_f32_e64 v35, v43, v53
	v_add_f32_e64 v34, v44, v34
	v_add_f32_e64 v35, v45, v35
	v_add_f32_e64 v34, v46, v34
	v_add_f32_e64 v35, v47, v35
	v_pk_add_f32 v[34:35], v[48:49], v[34:35]
	v_add_f32_e32 v34, v34, v35
	ds_bpermute_b32 v35, v165, v34
	s_cmp_ge_u32 s17, s18
	s_cbranch_scc1 .Ldma_f_mla2
	s_add_i32 s98, s6, 0xffffa800
	s_cmp_lg_u32 s44, 0
	s_cselect_b32 s98, s98, 0x10800
	v_readfirstlane_b32 s99, v107
	s_add_i32 m0, s99, s98
	v_readfirstlane_b32 s99, v93
	global_load_lds_dwordx4 v[102:103], off
	s_add_i32 m0, s99, s98
	v_readfirstlane_b32 s99, v108
	global_load_lds_dwordx4 v[100:101], off
	s_add_i32 m0, s99, s98
	s_nop 0
	global_load_lds_dwordx4 v[98:99], off

; template <int N> DI void wait_vmcnt() { asm volatile("s_waitcnt vmcnt(%0)" ::"n"(N) : "memory"); }
;     ...
;   asm volatile("s_waitcnt vmcnt(0)" ::: "memory");
; #pragma unroll
;   for (int t = 0; t < NST - 1; ++t)
;     if (t < ntile) FA_ISSUE(t, t)
;   int stage = 0;
;   for (int t = 0; t < ntile; ++t) {
;     int ahead = ((ntile < t + NST - 1) ? ntile : t + NST - 1) - (t + 1);
;     if (NST == 4 && ahead >= 2) wait_vmcnt<2 * NI>();
;     else if (ahead >= 1) wait_vmcnt<NI>();
;     else wait_vmcnt<0>();
;     raw_barrier();
;     if (t + NST - 1 < ntile) {
;       const int sn = (stage == 0) ? NST - 1 : stage - 1;
;       FA_ISSUE(t + NST - 1, sn)
;     }
.LBB0_488:
	s_or_b64 exec, exec, s[10:11]
	s_cmp_ge_u32 s17, s18
	s_cbranch_scc1 .Ldma_skip_mla2
	s_add_i32 s98, s6, 0xffffa800
	s_cmp_lg_u32 s44, 0
	s_cselect_b32 s98, s98, 0x10800
	v_readfirstlane_b32 s99, v107
	s_add_i32 m0, s99, s98
	v_readfirstlane_b32 s99, v93
	global_load_lds_dwordx4 v[102:103], off
	s_add_i32 m0, s99, s98
	v_readfirstlane_b32 s99, v108
	global_load_lds_dwordx4 v[100:101], off
	s_add_i32 m0, s99, s98
	s_nop 0
	global_load_lds_dwordx4 v[98:99], off

; #define MFMA(a, b, c) __builtin_amdgcn_mfma_f32_32x32x16_bf16((a), (b), (c), 0, 0, 0)
;     ...
;   float mc = m * c2;
;   if (MODE == 2) mc = selbit ? mc : 1e30f;
;   const f32x2v c2v = {c2, c2}, mcv = {-mc, -mc};
;   f32x2v rs2 = {0.f, 0.f};
; #pragma unroll
;   for (int ks = 0; ks < 2; ++ks)
; #pragma unroll
;     for (int st = 0; st < 2; ++st) {
;       union { unsigned u[4]; bf16x8 v; } pf;
; #pragma unroll
;       for (int j = 0; j < 4; ++j) {
;         const int i0 = 8 * st + 2 * j;
;         f32x2v t = {S[ks][i0], S[ks][i0 + 1]};
;         t = __builtin_elementwise_fma(t, c2v, mcv);
;         f32x2v pv;
;         if (variant == 1) { pv = t; } else {
;         pv.x = __builtin_amdgcn_exp2f(t.x);
;         pv.y = __builtin_amdgcn_exp2f(t.y);
;         }
;         if (MODE != 0) {
;           if (need_mask) {
;             pv.x = (S[ks][i0] > -1e29f) ? pv.x : 0.f;
;             pv.y = (S[ks][i0 + 1] > -1e29f) ? pv.y : 0.f;
;           }
;         }
;         rs2 += pv;
;         pf.u[j] = __builtin_bit_cast(unsigned, __builtin_convertvector(pv, hwbf16x2));
;       }
; #pragma unroll
;       for (int d = 0; d < DV / 32; ++d) {
;         const char* vp = base + C::KBYTES + (d * 32 + lr) * C::VSTR + (ks * 32 + 16 * st + 4 * lh) * 2;
;         const s16x4 lo = *(const s16x4*)vp, hi = *(const s16x4*)(vp + 16);
;         const bf16x8 vf = __builtin_shufflevector(lo, hi, 0, 1, 2, 3, 4, 5, 6, 7);
;         O[d] = MFMA(vf, pf.v, O[d]);
;       }
;     }
.LBB0_549:
	s_cmp_eq_u64 s[8:9], 0
	s_cbranch_scc1 .Lfast_sel2
	v_mul_f32_e32 v14, 0xbe38aa3b, v14
	v_cndmask_b32_e64 v14, v208, v14, s[10:11]
	v_pk_fma_f32 v[120:121], v[96:97], s[96:97], v[14:15] op_sel_hi:[1,0,0]
	v_cmp_lt_f32_e32 vcc, s33, v96
	v_exp_f32_e32 v119, v120
	v_exp_f32_e32 v120, v121
	v_cndmask_b32_e32 v96, 0, v119, vcc
	v_cmp_lt_f32_e32 vcc, s33, v97
	v_cndmask_b32_e64 v128, v119, v96, s[8:9]
	s_nop 0
	v_cndmask_b32_e32 v97, 0, v120, vcc
	v_cndmask_b32_e64 v129, v120, v97, s[8:9]
	v_pk_fma_f32 v[96:97], v[98:99], s[96:97], v[14:15] op_sel_hi:[1,0,0]
	v_cmp_lt_f32_e32 vcc, s33, v98
	v_exp_f32_e32 v96, v96
	v_exp_f32_e32 v97, v97
	v_cvt_pk_bf16_f32 v120, v128, v129
	v_cndmask_b32_e32 v98, 0, v96, vcc
	v_cmp_lt_f32_e32 vcc, s33, v99
	v_cndmask_b32_e64 v130, v96, v98, s[8:9]
	s_nop 0
	v_cndmask_b32_e32 v99, 0, v97, vcc
	v_cndmask_b32_e64 v131, v97, v99, s[8:9]
	v_pk_fma_f32 v[96:97], v[100:101], s[96:97], v[14:15] op_sel_hi:[1,0,0]
	v_cmp_lt_f32_e32 vcc, s33, v100
	v_exp_f32_e32 v96, v96
	v_exp_f32_e32 v97, v97
	v_cvt_pk_bf16_f32 v121, v130, v131
	v_cndmask_b32_e32 v98, 0, v96, vcc
	v_cmp_lt_f32_e32 vcc, s33, v101
	v_cndmask_b32_e64 v132, v96, v98, s[8:9]
	s_nop 0
	v_cndmask_b32_e32 v99, 0, v97, vcc
	v_cndmask_b32_e64 v133, v97, v99, s[8:9]
	v_pk_fma_f32 v[96:97], v[102:103], s[96:97], v[14:15] op_sel_hi:[1,0,0]
	v_cmp_lt_f32_e32 vcc, s33, v102
	v_exp_f32_e32 v96, v96
	v_exp_f32_e32 v97, v97
	v_cvt_pk_bf16_f32 v122, v132, v133
	v_cndmask_b32_e32 v98, 0, v96, vcc
	v_cmp_lt_f32_e32 vcc, s33, v103
	v_cndmask_b32_e64 v102, v96, v98, s[8:9]
	s_nop 0
	v_cndmask_b32_e32 v99, 0, v97, vcc
	v_cndmask_b32_e64 v103, v97, v99, s[8:9]
	s_nop 0
	s_nop 0
	s_nop 0
	s_nop 0
	v_cvt_pk_bf16_f32 v123, v102, v103
	s_nop 0
	v_cmp_lt_f32_e32 vcc, s33, v104
	s_waitcnt lgkmcnt(0)
	v_mfma_f32_32x32x16_bf16 v[64:79], v[216:219], v[120:123], v[64:79]
	s_nop 0
	s_waitcnt lgkmcnt(0)
	v_mfma_f32_32x32x16_bf16 v[48:63], v[220:223], v[120:123], v[48:63]
	v_add_f32_e64 v98, v128, 0
	v_add_f32_e64 v99, v129, 0
	v_add_f32_e64 v98, v130, v98
	v_add_f32_e64 v99, v131, v99
	v_add_f32_e64 v98, v132, v98
	v_add_f32_e64 v99, v133, v99
	v_pk_add_f32 v[120:121], v[102:103], v[98:99]
	v_pk_fma_f32 v[98:99], v[104:105], s[96:97], v[14:15] op_sel_hi:[1,0,0]
	s_nop 0
	v_exp_f32_e32 v98, v98
	v_exp_f32_e32 v99, v99
	v_cndmask_b32_e32 v100, 0, v98, vcc
	v_cmp_lt_f32_e32 vcc, s33, v105
	v_cndmask_b32_e64 v122, v98, v100, s[8:9]
	s_nop 0
	v_cndmask_b32_e32 v101, 0, v99, vcc
	v_cndmask_b32_e64 v123, v99, v101, s[8:9]
	v_pk_fma_f32 v[100:101], v[106:107], s[96:97], v[14:15] op_sel_hi:[1,0,0]
	v_cmp_lt_f32_e32 vcc, s33, v106
	v_exp_f32_e32 v99, v100
	v_exp_f32_e32 v100, v101
	v_cvt_pk_bf16_f32 v98, v122, v123
	v_cndmask_b32_e32 v101, 0, v99, vcc
	v_cmp_lt_f32_e32 vcc, s33, v107
	v_cndmask_b32_e64 v106, v99, v101, s[8:9]
	s_nop 0
	v_cndmask_b32_e32 v102, 0, v100, vcc
	v_cndmask_b32_e64 v107, v100, v102, s[8:9]
	v_pk_fma_f32 v[100:101], v[108:109], s[96:97], v[14:15] op_sel_hi:[1,0,0]
	v_cmp_lt_f32_e32 vcc, s33, v108
	v_exp_f32_e32 v100, v100
	v_exp_f32_e32 v101, v101
	v_cvt_pk_bf16_f32 v99, v106, v107
	v_cndmask_b32_e32 v102, 0, v100, vcc
	v_cmp_lt_f32_e32 vcc, s33, v109
	v_cndmask_b32_e64 v108, v100, v102, s[8:9]
	s_nop 0
	v_cndmask_b32_e32 v103, 0, v101, vcc
	v_cndmask_b32_e64 v109, v101, v103, s[8:9]
	v_pk_fma_f32 v[102:103], v[110:111], s[96:97], v[14:15] op_sel_hi:[1,0,0]
	v_cmp_lt_f32_e32 vcc, s33, v110
	v_exp_f32_e32 v101, v102
	v_exp_f32_e32 v102, v103
	v_cvt_pk_bf16_f32 v100, v108, v109
	v_cndmask_b32_e32 v103, 0, v101, vcc
	v_cmp_lt_f32_e32 vcc, s33, v111
	v_cndmask_b32_e64 v110, v101, v103, s[8:9]
	s_nop 0
	v_cndmask_b32_e32 v104, 0, v102, vcc
	v_cndmask_b32_e64 v111, v102, v104, s[8:9]
	s_nop 0
	v_cvt_pk_bf16_f32 v101, v110, v111
	v_cmp_lt_f32_e32 vcc, s33, v80
	s_nop 0
	v_mfma_f32_32x32x16_bf16 v[64:79], v[224:227], v[98:101], v[64:79]
	s_waitcnt lgkmcnt(0)
; #define MFMA(a, b, c) __builtin_amdgcn_mfma_f32_32x32x16_bf16((a), (b), (c), 0, 0, 0)
; template <int N> DI void wait_vmcnt() { asm volatile("s_waitcnt vmcnt(%0)" ::"n"(N) : "memory"); }
;     ...
; #pragma unroll
;       for (int j = 0; j < 4; ++j) {
;         const int i0 = 8 * st + 2 * j;
;         f32x2v t = {S[ks][i0], S[ks][i0 + 1]};
;         t = __builtin_elementwise_fma(t, c2v, mcv);
;         f32x2v pv;
;         if (variant == 1) { pv = t; } else {
;         pv.x = __builtin_amdgcn_exp2f(t.x);
;         pv.y = __builtin_amdgcn_exp2f(t.y);
;         }
;         if (MODE != 0) {
;           if (need_mask) {
;             pv.x = (S[ks][i0] > -1e29f) ? pv.x : 0.f;
;             pv.y = (S[ks][i0 + 1] > -1e29f) ? pv.y : 0.f;
;           }
;         }
;         rs2 += pv;
;         pf.u[j] = __builtin_bit_cast(unsigned, __builtin_convertvector(pv, hwbf16x2));
;       }
; #pragma unroll
;       for (int d = 0; d < DV / 32; ++d) {
;         const char* vp = base + C::KBYTES + (d * 32 + lr) * C::VSTR + (ks * 32 + 16 * st + 4 * lh) * 2;
;         const s16x4 lo = *(const s16x4*)vp, hi = *(const s16x4*)(vp + 16);
;         const bf16x8 vf = __builtin_shufflevector(lo, hi, 0, 1, 2, 3, 4, 5, 6, 7);
;         O[d] = MFMA(vf, pf.v, O[d]);
;       }
;     }
;   float rs = rs2.x + rs2.y;
;   rs += __shfl_xor(rs, 32);
;     ...
;   asm volatile("s_waitcnt vmcnt(0)" ::: "memory");
; #pragma unroll
;   for (int t = 0; t < NST - 1; ++t)
;     if (t < ntile) FA_ISSUE(t, t)
;   int stage = 0;
;   for (int t = 0; t < ntile; ++t) {
;     int ahead = ((ntile < t + NST - 1) ? ntile : t + NST - 1) - (t + 1);
;     if (NST == 4 && ahead >= 2) wait_vmcnt<2 * NI>();
;     else if (ahead >= 1) wait_vmcnt<NI>();
;     else wait_vmcnt<0>();
;     raw_barrier();
;     if (t + NST - 1 < ntile) {
;       const int sn = (stage == 0) ? NST - 1 : stage - 1;
;       FA_ISSUE(t + NST - 1, sn)
	v_mfma_f32_32x32x16_bf16 v[48:63], v[228:231], v[98:101], v[48:63]
	v_fma_f32 v100, v80, s96, v14
	v_fma_f32 v101, v81, s96, v14
	v_fma_f32 v102, v82, s96, v14
	v_fma_f32 v103, v83, s96, v14
	v_exp_f32_e32 v100, v100
	v_exp_f32_e32 v101, v101
	v_pk_add_f32 v[98:99], v[122:123], v[120:121]
	v_cndmask_b32_e32 v80, 0, v100, vcc
	v_cmp_lt_f32_e32 vcc, s33, v81
	v_pk_add_f32 v[98:99], v[106:107], v[98:99]
	v_cndmask_b32_e64 v100, v100, v80, s[8:9]
	v_cndmask_b32_e32 v81, 0, v101, vcc
	v_cndmask_b32_e64 v101, v101, v81, s[8:9]
	v_exp_f32_e32 v81, v102
	v_exp_f32_e32 v102, v103
	v_cmp_lt_f32_e32 vcc, s33, v82
	v_cvt_pk_bf16_f32 v80, v100, v101
	v_pk_add_f32 v[98:99], v[108:109], v[98:99]
	v_cndmask_b32_e32 v82, 0, v81, vcc
	v_cmp_lt_f32_e32 vcc, s33, v83
	v_pk_add_f32 v[98:99], v[110:111], v[98:99]
	s_nop 0
	v_cndmask_b32_e32 v83, 0, v102, vcc
	v_cndmask_b32_e64 v103, v102, v83, s[8:9]
	v_cndmask_b32_e64 v102, v81, v82, s[8:9]
	v_pk_fma_f32 v[82:83], v[84:85], s[96:97], v[14:15] op_sel_hi:[1,0,0]
	v_cmp_lt_f32_e32 vcc, s33, v84
	v_exp_f32_e32 v82, v82
	v_exp_f32_e32 v83, v83
	v_cvt_pk_bf16_f32 v81, v102, v103
	v_cndmask_b32_e32 v84, 0, v82, vcc
	v_cmp_lt_f32_e32 vcc, s33, v85
	v_cndmask_b32_e64 v104, v82, v84, s[8:9]
	s_nop 0
	v_cndmask_b32_e32 v85, 0, v83, vcc
	v_cndmask_b32_e64 v105, v83, v85, s[8:9]
	v_pk_fma_f32 v[84:85], v[86:87], s[96:97], v[14:15] op_sel_hi:[1,0,0]
	v_cmp_lt_f32_e32 vcc, s33, v86
	v_exp_f32_e32 v83, v84
	v_exp_f32_e32 v84, v85
	v_cvt_pk_bf16_f32 v82, v104, v105
	v_cndmask_b32_e32 v85, 0, v83, vcc
	v_cmp_lt_f32_e32 vcc, s33, v87
	v_cndmask_b32_e64 v106, v83, v85, s[8:9]
	s_nop 0
	v_cndmask_b32_e32 v86, 0, v84, vcc
	v_cndmask_b32_e64 v107, v84, v86, s[8:9]
	s_nop 0
	v_cvt_pk_bf16_f32 v83, v106, v107
	v_cmp_lt_f32_e32 vcc, s33, v88
	s_waitcnt lgkmcnt(0)
	v_mfma_f32_32x32x16_bf16 v[64:79], v[232:235], v[80:83], v[64:79]
	s_nop 0
	s_waitcnt lgkmcnt(0)
	v_mfma_f32_32x32x16_bf16 v[48:63], v[236:239], v[80:83], v[48:63]
	v_add_f32_e64 v80, v100, v98
	v_add_f32_e64 v81, v101, v99
	v_add_f32_e64 v80, v102, v80
	v_add_f32_e64 v81, v103, v81
	v_add_f32_e64 v80, v104, v80
	v_add_f32_e64 v81, v105, v81
	v_pk_add_f32 v[98:99], v[106:107], v[80:81]
	v_pk_fma_f32 v[80:81], v[88:89], s[96:97], v[14:15] op_sel_hi:[1,0,0]
	s_nop 0
	v_exp_f32_e32 v80, v80
	v_exp_f32_e32 v81, v81
	v_cndmask_b32_e32 v82, 0, v80, vcc
	v_cmp_lt_f32_e32 vcc, s33, v89
	v_cndmask_b32_e64 v88, v80, v82, s[8:9]
	s_nop 0
	v_cndmask_b32_e32 v83, 0, v81, vcc
	v_cndmask_b32_e64 v89, v81, v83, s[8:9]
	v_pk_fma_f32 v[82:83], v[90:91], s[96:97], v[14:15] op_sel_hi:[1,0,0]
	v_cmp_lt_f32_e32 vcc, s33, v90
	v_exp_f32_e32 v81, v82
	v_exp_f32_e32 v82, v83
	v_cvt_pk_bf16_f32 v80, v88, v89
	v_cndmask_b32_e32 v83, 0, v81, vcc
	v_cmp_lt_f32_e32 vcc, s33, v91
	v_cndmask_b32_e64 v90, v81, v83, s[8:9]
	s_nop 0
	v_cndmask_b32_e32 v84, 0, v82, vcc
	v_cndmask_b32_e64 v91, v82, v84, s[8:9]
	v_pk_fma_f32 v[82:83], v[92:93], s[96:97], v[14:15] op_sel_hi:[1,0,0]
	v_cmp_lt_f32_e32 vcc, s33, v92
	v_exp_f32_e32 v82, v82
	v_exp_f32_e32 v83, v83
	v_cvt_pk_bf16_f32 v81, v90, v91
	v_cndmask_b32_e32 v84, 0, v82, vcc
	v_cmp_lt_f32_e32 vcc, s33, v93
	v_cndmask_b32_e64 v92, v82, v84, s[8:9]
	s_nop 0
	v_cndmask_b32_e32 v85, 0, v83, vcc
	v_cndmask_b32_e64 v93, v83, v85, s[8:9]
	v_pk_fma_f32 v[84:85], v[94:95], s[96:97], v[14:15] op_sel_hi:[1,0,0]
	v_cmp_lt_f32_e32 vcc, s33, v94
	v_exp_f32_e32 v14, v84
	v_exp_f32_e32 v83, v85
	v_cvt_pk_bf16_f32 v82, v92, v93
	v_cndmask_b32_e32 v84, 0, v14, vcc
	v_cmp_lt_f32_e32 vcc, s33, v95
	v_cndmask_b32_e64 v94, v14, v84, s[8:9]
	s_nop 0
	v_cndmask_b32_e32 v85, 0, v83, vcc
	v_cndmask_b32_e64 v95, v83, v85, s[8:9]
	s_nop 0
	v_cvt_pk_bf16_f32 v83, v94, v95
	s_waitcnt lgkmcnt(0)
	s_nop 0
	v_mfma_f32_32x32x16_bf16 v[64:79], v[240:243], v[80:83], v[64:79]
	s_nop 0
	s_waitcnt lgkmcnt(0)
	v_mfma_f32_32x32x16_bf16 v[48:63], v[244:247], v[80:83], v[48:63]
	v_add_f32_e64 v80, v88, v98
	v_add_f32_e64 v81, v89, v99
	v_add_f32_e64 v80, v90, v80
	v_add_f32_e64 v81, v91, v81
	v_add_f32_e64 v80, v92, v80
	v_add_f32_e64 v81, v93, v81
	v_pk_add_f32 v[80:81], v[94:95], v[80:81]
	s_nop 0
	v_add_f32_e32 v14, v80, v81
	ds_bpermute_b32 v80, v165, v14
	s_add_i32 s98, s0, 3
	s_cmp_gt_u32 s98, s41
	s_cbranch_scc1 .Ldma_m_sel2
	s_add_i32 s98, s6, 0xffffb800
	s_cmp_lg_u32 s45, 0
	s_cselect_b32 s98, s98, 0xd800
	v_readfirstlane_b32 s99, v112
	s_add_i32 m0, s99, s98
	v_readfirstlane_b32 s99, v15
	global_load_lds_dwordx4 v[12:13], off
	s_add_i32 m0, s99, s98
	v_readfirstlane_b32 s99, v113
	global_load_lds_dwordx4 v[10:11], off
	s_add_i32 m0, s99, s98
	s_nop 0
	global_load_lds_dwordx4 v[8:9], off

; #define MFMA(a, b, c) __builtin_amdgcn_mfma_f32_32x32x16_bf16((a), (b), (c), 0, 0, 0)
; template <int N> DI void wait_vmcnt() { asm volatile("s_waitcnt vmcnt(%0)" ::"n"(N) : "memory"); }
;     ...
;   float mc = m * c2;
;   if (MODE == 2) mc = selbit ? mc : 1e30f;
;   const f32x2v c2v = {c2, c2}, mcv = {-mc, -mc};
;   f32x2v rs2 = {0.f, 0.f};
; #pragma unroll
;   for (int ks = 0; ks < 2; ++ks)
; #pragma unroll
;     for (int st = 0; st < 2; ++st) {
;       union { unsigned u[4]; bf16x8 v; } pf;
; #pragma unroll
;       for (int j = 0; j < 4; ++j) {
;         const int i0 = 8 * st + 2 * j;
;         f32x2v t = {S[ks][i0], S[ks][i0 + 1]};
;         t = __builtin_elementwise_fma(t, c2v, mcv);
;         f32x2v pv;
;         if (variant == 1) { pv = t; } else {
;         pv.x = __builtin_amdgcn_exp2f(t.x);
;         pv.y = __builtin_amdgcn_exp2f(t.y);
;         }
;         if (MODE != 0) {
;           if (need_mask) {
;             pv.x = (S[ks][i0] > -1e29f) ? pv.x : 0.f;
;             pv.y = (S[ks][i0 + 1] > -1e29f) ? pv.y : 0.f;
;           }
;         }
;         rs2 += pv;
;         pf.u[j] = __builtin_bit_cast(unsigned, __builtin_convertvector(pv, hwbf16x2));
;       }
; #pragma unroll
;       for (int d = 0; d < DV / 32; ++d) {
;         const char* vp = base + C::KBYTES + (d * 32 + lr) * C::VSTR + (ks * 32 + 16 * st + 4 * lh) * 2;
;         const s16x4 lo = *(const s16x4*)vp, hi = *(const s16x4*)(vp + 16);
;         const bf16x8 vf = __builtin_shufflevector(lo, hi, 0, 1, 2, 3, 4, 5, 6, 7);
;         O[d] = MFMA(vf, pf.v, O[d]);
;       }
;     }
;   float rs = rs2.x + rs2.y;
;   rs += __shfl_xor(rs, 32);
;     ...
;   asm volatile("s_waitcnt vmcnt(0)" ::: "memory");
; #pragma unroll
;   for (int t = 0; t < NST - 1; ++t)
;     if (t < ntile) FA_ISSUE(t, t)
;   int stage = 0;
;   for (int t = 0; t < ntile; ++t) {
;     int ahead = ((ntile < t + NST - 1) ? ntile : t + NST - 1) - (t + 1);
;     if (NST == 4 && ahead >= 2) wait_vmcnt<2 * NI>();
;     else if (ahead >= 1) wait_vmcnt<NI>();
;     else wait_vmcnt<0>();
;     raw_barrier();
;     if (t + NST - 1 < ntile) {
;       const int sn = (stage == 0) ? NST - 1 : stage - 1;
;       FA_ISSUE(t + NST - 1, sn)
.Lfast_sel2:
	v_mul_f32_e32 v14, 0xbe38aa3b, v14
	v_cndmask_b32_e64 v14, v208, v14, s[10:11]
	v_pk_fma_f32 v[120:121], v[96:97], s[96:97], v[14:15] op_sel_hi:[1,0,0]
	v_exp_f32_e32 v128, v120
	v_exp_f32_e32 v129, v121
	v_pk_fma_f32 v[96:97], v[98:99], s[96:97], v[14:15] op_sel_hi:[1,0,0]
	v_exp_f32_e32 v130, v96
	v_exp_f32_e32 v131, v97
	v_cvt_pk_bf16_f32 v120, v128, v129
	v_pk_fma_f32 v[96:97], v[100:101], s[96:97], v[14:15] op_sel_hi:[1,0,0]
	v_exp_f32_e32 v132, v96
	v_exp_f32_e32 v133, v97
	v_cvt_pk_bf16_f32 v121, v130, v131
	v_pk_fma_f32 v[96:97], v[102:103], s[96:97], v[14:15] op_sel_hi:[1,0,0]
	v_exp_f32_e32 v102, v96
	v_exp_f32_e32 v103, v97
	v_cvt_pk_bf16_f32 v122, v132, v133
	v_cvt_pk_bf16_f32 v123, v102, v103
	s_waitcnt lgkmcnt(0)
	s_nop 0
	v_mfma_f32_32x32x16_bf16 v[64:79], v[216:219], v[120:123], v[64:79]
	s_waitcnt lgkmcnt(0)
	v_mfma_f32_32x32x16_bf16 v[48:63], v[220:223], v[120:123], v[48:63]
	v_add_f32_e64 v98, v128, 0
	v_add_f32_e64 v99, v129, 0
	v_add_f32_e64 v98, v130, v98
	v_add_f32_e64 v99, v131, v99
	v_add_f32_e64 v98, v132, v98
	v_add_f32_e64 v99, v133, v99
	v_pk_add_f32 v[120:121], v[102:103], v[98:99]
	v_pk_fma_f32 v[98:99], v[104:105], s[96:97], v[14:15] op_sel_hi:[1,0,0]
	v_exp_f32_e32 v122, v98
	v_exp_f32_e32 v123, v99
	v_pk_fma_f32 v[100:101], v[106:107], s[96:97], v[14:15] op_sel_hi:[1,0,0]
	v_exp_f32_e32 v106, v100
	v_exp_f32_e32 v107, v101
	v_cvt_pk_bf16_f32 v98, v122, v123
	v_pk_fma_f32 v[100:101], v[108:109], s[96:97], v[14:15] op_sel_hi:[1,0,0]
	v_exp_f32_e32 v108, v100
	v_exp_f32_e32 v109, v101
	v_cvt_pk_bf16_f32 v99, v106, v107
	v_pk_fma_f32 v[102:103], v[110:111], s[96:97], v[14:15] op_sel_hi:[1,0,0]
	v_exp_f32_e32 v110, v102
	v_exp_f32_e32 v111, v103
	v_cvt_pk_bf16_f32 v100, v108, v109
	v_cvt_pk_bf16_f32 v101, v110, v111
	s_nop 1
	v_mfma_f32_32x32x16_bf16 v[64:79], v[224:227], v[98:101], v[64:79]
	s_waitcnt lgkmcnt(0)
	v_mfma_f32_32x32x16_bf16 v[48:63], v[228:231], v[98:101], v[48:63]
	v_fma_f32 v100, v80, s96, v14
	v_fma_f32 v101, v81, s96, v14
	v_fma_f32 v102, v82, s96, v14
	v_fma_f32 v103, v83, s96, v14
	v_exp_f32_e32 v100, v100
	v_exp_f32_e32 v101, v101
	v_pk_add_f32 v[98:99], v[122:123], v[120:121]
	v_pk_add_f32 v[98:99], v[106:107], v[98:99]
	v_exp_f32_e32 v102, v102
	v_exp_f32_e32 v103, v103
	v_cvt_pk_bf16_f32 v80, v100, v101
	v_pk_add_f32 v[98:99], v[108:109], v[98:99]
	v_pk_add_f32 v[98:99], v[110:111], v[98:99]
	v_pk_fma_f32 v[82:83], v[84:85], s[96:97], v[14:15] op_sel_hi:[1,0,0]
	v_exp_f32_e32 v104, v82
	v_exp_f32_e32 v105, v83
	v_cvt_pk_bf16_f32 v81, v102, v103
	v_pk_fma_f32 v[84:85], v[86:87], s[96:97], v[14:15] op_sel_hi:[1,0,0]
	v_exp_f32_e32 v106, v84
	v_exp_f32_e32 v107, v85
	v_cvt_pk_bf16_f32 v82, v104, v105
	v_cvt_pk_bf16_f32 v83, v106, v107
	s_waitcnt lgkmcnt(0)
	s_nop 0
	v_mfma_f32_32x32x16_bf16 v[64:79], v[232:235], v[80:83], v[64:79]
	s_waitcnt lgkmcnt(0)
	v_mfma_f32_32x32x16_bf16 v[48:63], v[236:239], v[80:83], v[48:63]
	v_add_f32_e64 v80, v100, v98
	v_add_f32_e64 v81, v101, v99
	v_add_f32_e64 v80, v102, v80
	v_add_f32_e64 v81, v103, v81
	v_add_f32_e64 v80, v104, v80
	v_add_f32_e64 v81, v105, v81
	v_pk_add_f32 v[98:99], v[106:107], v[80:81]
	v_pk_fma_f32 v[80:81], v[88:89], s[96:97], v[14:15] op_sel_hi:[1,0,0]
	v_exp_f32_e32 v88, v80
	v_exp_f32_e32 v89, v81
	v_pk_fma_f32 v[82:83], v[90:91], s[96:97], v[14:15] op_sel_hi:[1,0,0]
	v_exp_f32_e32 v90, v82
	v_exp_f32_e32 v91, v83
	v_cvt_pk_bf16_f32 v80, v88, v89
	v_pk_fma_f32 v[82:83], v[92:93], s[96:97], v[14:15] op_sel_hi:[1,0,0]
	v_exp_f32_e32 v92, v82
	v_exp_f32_e32 v93, v83
	v_cvt_pk_bf16_f32 v81, v90, v91
	v_pk_fma_f32 v[84:85], v[94:95], s[96:97], v[14:15] op_sel_hi:[1,0,0]
	v_exp_f32_e32 v94, v84
	v_exp_f32_e32 v95, v85
	v_cvt_pk_bf16_f32 v82, v92, v93
	v_cvt_pk_bf16_f32 v83, v94, v95
	s_waitcnt lgkmcnt(0)
	s_nop 0
	v_mfma_f32_32x32x16_bf16 v[64:79], v[240:243], v[80:83], v[64:79]
	s_waitcnt lgkmcnt(0)
	v_mfma_f32_32x32x16_bf16 v[48:63], v[244:247], v[80:83], v[48:63]
	v_add_f32_e64 v80, v88, v98
	v_add_f32_e64 v81, v89, v99
	v_add_f32_e64 v80, v90, v80
	v_add_f32_e64 v81, v91, v81
	v_add_f32_e64 v80, v92, v80
	v_add_f32_e64 v81, v93, v81
	v_pk_add_f32 v[80:81], v[94:95], v[80:81]
	v_add_f32_e32 v14, v80, v81
	ds_bpermute_b32 v80, v165, v14
	s_add_i32 s98, s0, 3
	s_cmp_gt_u32 s98, s41
	s_cbranch_scc1 .Ldma_f_sel2
	s_add_i32 s98, s6, 0xffffb800
	s_cmp_lg_u32 s45, 0
	s_cselect_b32 s98, s98, 0xd800
	v_readfirstlane_b32 s99, v112
	s_add_i32 m0, s99, s98
	v_readfirstlane_b32 s99, v15
	global_load_lds_dwordx4 v[12:13], off
	s_add_i32 m0, s99, s98
	v_readfirstlane_b32 s99, v113
	global_load_lds_dwordx4 v[10:11], off
	s_add_i32 m0, s99, s98
	s_nop 0
	global_load_lds_dwordx4 v[8:9], off

; template <int N> DI void wait_vmcnt() { asm volatile("s_waitcnt vmcnt(%0)" ::"n"(N) : "memory"); }
;     ...
;   asm volatile("s_waitcnt vmcnt(0)" ::: "memory");
; #pragma unroll
;   for (int t = 0; t < NST - 1; ++t)
;     if (t < ntile) FA_ISSUE(t, t)
;   int stage = 0;
;   for (int t = 0; t < ntile; ++t) {
;     int ahead = ((ntile < t + NST - 1) ? ntile : t + NST - 1) - (t + 1);
;     if (NST == 4 && ahead >= 2) wait_vmcnt<2 * NI>();
;     else if (ahead >= 1) wait_vmcnt<NI>();
;     else wait_vmcnt<0>();
;     raw_barrier();
;     if (t + NST - 1 < ntile) {
;       const int sn = (stage == 0) ? NST - 1 : stage - 1;
;       FA_ISSUE(t + NST - 1, sn)
;     }
.LBB0_550:
	s_add_i32 s98, s0, 3
	s_cmp_gt_u32 s98, s41
	s_cbranch_scc1 .Ldma_skip_sel2
	s_add_i32 s98, s6, 0xffffb800
	s_cmp_lg_u32 s45, 0
	s_cselect_b32 s98, s98, 0xd800
	v_readfirstlane_b32 s99, v112
	s_add_i32 m0, s99, s98
	v_readfirstlane_b32 s99, v15
	global_load_lds_dwordx4 v[12:13], off
	s_add_i32 m0, s99, s98
	v_readfirstlane_b32 s99, v113
	global_load_lds_dwordx4 v[10:11], off
	s_add_i32 m0, s99, s98
	s_nop 0
	global_load_lds_dwordx4 v[8:9], off

; #define MFMA(a, b, c) __builtin_amdgcn_mfma_f32_32x32x16_bf16((a), (b), (c), 0, 0, 0)
;     ...
;   float mc = m * c2;
;   if (MODE == 2) mc = selbit ? mc : 1e30f;
;   const f32x2v c2v = {c2, c2}, mcv = {-mc, -mc};
;   f32x2v rs2 = {0.f, 0.f};
; #pragma unroll
;   for (int ks = 0; ks < 2; ++ks)
; #pragma unroll
;     for (int st = 0; st < 2; ++st) {
;       union { unsigned u[4]; bf16x8 v; } pf;
; #pragma unroll
;       for (int j = 0; j < 4; ++j) {
;         const int i0 = 8 * st + 2 * j;
;         f32x2v t = {S[ks][i0], S[ks][i0 + 1]};
;         t = __builtin_elementwise_fma(t, c2v, mcv);
;         f32x2v pv;
;         if (variant == 1) { pv = t; } else {
;         pv.x = __builtin_amdgcn_exp2f(t.x);
;         pv.y = __builtin_amdgcn_exp2f(t.y);
;         }
;         if (MODE != 0) {
;           if (need_mask) {
;             pv.x = (S[ks][i0] > -1e29f) ? pv.x : 0.f;
;             pv.y = (S[ks][i0 + 1] > -1e29f) ? pv.y : 0.f;
;           }
;         }
;         rs2 += pv;
;         pf.u[j] = __builtin_bit_cast(unsigned, __builtin_convertvector(pv, hwbf16x2));
;       }
; #pragma unroll
;       for (int d = 0; d < DV / 32; ++d) {
;         const char* vp = base + C::KBYTES + (d * 32 + lr) * C::VSTR + (ks * 32 + 16 * st + 4 * lh) * 2;
;         const s16x4 lo = *(const s16x4*)vp, hi = *(const s16x4*)(vp + 16);
;         const bf16x8 vf = __builtin_shufflevector(lo, hi, 0, 1, 2, 3, 4, 5, 6, 7);
;         O[d] = MFMA(vf, pf.v, O[d]);
;       }
;     }
.LBB0_585:
	s_cmp_eq_u64 s[8:9], 0
	s_cbranch_scc1 .Lfast_win2
	v_mul_f32_e32 v12, 0xbe38aa3b, v12
	v_pk_fma_f32 v[176:177], v[128:129], s[96:97], v[12:13] op_sel_hi:[1,0,0]
	v_cmp_lt_f32_e32 vcc, s33, v128
	v_exp_f32_e32 v176, v176
	v_exp_f32_e32 v177, v177
	v_cndmask_b32_e32 v128, 0, v176, vcc
	v_cmp_lt_f32_e32 vcc, s33, v129
	v_cndmask_b32_e64 v184, v176, v128, s[8:9]
	s_nop 0
	v_cndmask_b32_e32 v129, 0, v177, vcc
	v_cndmask_b32_e64 v185, v177, v129, s[8:9]
	v_pk_fma_f32 v[128:129], v[130:131], s[96:97], v[12:13] op_sel_hi:[1,0,0]
	v_cmp_lt_f32_e32 vcc, s33, v130
	v_exp_f32_e32 v128, v128
	v_exp_f32_e32 v129, v129
	v_cvt_pk_bf16_f32 v176, v184, v185
	v_cndmask_b32_e32 v130, 0, v128, vcc
	v_cmp_lt_f32_e32 vcc, s33, v131
	v_cndmask_b32_e64 v186, v128, v130, s[8:9]
	s_nop 0
	v_cndmask_b32_e32 v131, 0, v129, vcc
	v_cndmask_b32_e64 v187, v129, v131, s[8:9]
	v_pk_fma_f32 v[128:129], v[132:133], s[96:97], v[12:13] op_sel_hi:[1,0,0]
	v_cmp_lt_f32_e32 vcc, s33, v132
	v_exp_f32_e32 v128, v128
	v_exp_f32_e32 v129, v129
	v_cvt_pk_bf16_f32 v177, v186, v187
	v_cndmask_b32_e32 v130, 0, v128, vcc
	v_cmp_lt_f32_e32 vcc, s33, v133
	v_cndmask_b32_e64 v188, v128, v130, s[8:9]
	s_nop 0
	v_cndmask_b32_e32 v131, 0, v129, vcc
	v_cndmask_b32_e64 v189, v129, v131, s[8:9]
	v_pk_fma_f32 v[128:129], v[134:135], s[96:97], v[12:13] op_sel_hi:[1,0,0]
	v_cmp_lt_f32_e32 vcc, s33, v134
	v_exp_f32_e32 v128, v128
	v_exp_f32_e32 v129, v129
	v_cvt_pk_bf16_f32 v178, v188, v189
	v_cndmask_b32_e32 v130, 0, v128, vcc
	v_cmp_lt_f32_e32 vcc, s33, v135
	v_cndmask_b32_e64 v134, v128, v130, s[8:9]
	s_nop 0
	v_cndmask_b32_e32 v131, 0, v129, vcc
	v_cndmask_b32_e64 v135, v129, v131, s[8:9]
	s_nop 0
	s_nop 0
	s_nop 0
	s_nop 0
	v_cvt_pk_bf16_f32 v179, v134, v135
	s_nop 0
	v_cmp_lt_f32_e32 vcc, s33, v136
	s_waitcnt lgkmcnt(0)
	v_mfma_f32_32x32x16_bf16 v[96:111], v[216:219], v[176:179], v[96:111]
	s_nop 0
	s_waitcnt lgkmcnt(0)
	v_mfma_f32_32x32x16_bf16 v[80:95], v[220:223], v[176:179], v[80:95]
	v_add_f32_e64 v130, v184, 0
	v_add_f32_e64 v131, v185, 0
	v_add_f32_e64 v130, v186, v130
	v_add_f32_e64 v131, v187, v131
	v_add_f32_e64 v130, v188, v130
	v_add_f32_e64 v131, v189, v131
	v_pk_add_f32 v[176:177], v[134:135], v[130:131]
	v_pk_fma_f32 v[130:131], v[136:137], s[96:97], v[12:13] op_sel_hi:[1,0,0]
	s_nop 0
	v_exp_f32_e32 v130, v130
	v_exp_f32_e32 v131, v131
	v_cndmask_b32_e32 v132, 0, v130, vcc
	v_cmp_lt_f32_e32 vcc, s33, v137
	v_cndmask_b32_e64 v178, v130, v132, s[8:9]
	s_nop 0
	v_cndmask_b32_e32 v133, 0, v131, vcc
	v_cndmask_b32_e64 v179, v131, v133, s[8:9]
	v_pk_fma_f32 v[132:133], v[138:139], s[96:97], v[12:13] op_sel_hi:[1,0,0]
	v_cmp_lt_f32_e32 vcc, s33, v138
	v_exp_f32_e32 v131, v132
	v_exp_f32_e32 v132, v133
	v_cvt_pk_bf16_f32 v130, v178, v179
	v_cndmask_b32_e32 v133, 0, v131, vcc
	v_cmp_lt_f32_e32 vcc, s33, v139
	v_cndmask_b32_e64 v138, v131, v133, s[8:9]
	s_nop 0
	v_cndmask_b32_e32 v134, 0, v132, vcc
	v_cndmask_b32_e64 v139, v132, v134, s[8:9]
	v_pk_fma_f32 v[132:133], v[140:141], s[96:97], v[12:13] op_sel_hi:[1,0,0]
	v_cmp_lt_f32_e32 vcc, s33, v140
	v_exp_f32_e32 v132, v132
	v_exp_f32_e32 v133, v133
	v_cvt_pk_bf16_f32 v131, v138, v139
	v_cndmask_b32_e32 v134, 0, v132, vcc
	v_cmp_lt_f32_e32 vcc, s33, v141
	v_cndmask_b32_e64 v140, v132, v134, s[8:9]
	s_nop 0
	v_cndmask_b32_e32 v135, 0, v133, vcc
	v_cndmask_b32_e64 v141, v133, v135, s[8:9]
	v_pk_fma_f32 v[134:135], v[142:143], s[96:97], v[12:13] op_sel_hi:[1,0,0]
	v_cmp_lt_f32_e32 vcc, s33, v142
	v_exp_f32_e32 v133, v134
	v_exp_f32_e32 v134, v135
	v_cvt_pk_bf16_f32 v132, v140, v141
	v_cndmask_b32_e32 v135, 0, v133, vcc
	v_cmp_lt_f32_e32 vcc, s33, v143
	v_cndmask_b32_e64 v142, v133, v135, s[8:9]
	s_nop 0
	v_cndmask_b32_e32 v136, 0, v134, vcc
	v_cndmask_b32_e64 v143, v134, v136, s[8:9]
	s_nop 0
	v_cvt_pk_bf16_f32 v133, v142, v143
	v_cmp_lt_f32_e32 vcc, s33, v112
	s_nop 0
	v_mfma_f32_32x32x16_bf16 v[96:111], v[224:227], v[130:133], v[96:111]
	s_waitcnt lgkmcnt(0)
; #define MFMA(a, b, c) __builtin_amdgcn_mfma_f32_32x32x16_bf16((a), (b), (c), 0, 0, 0)
;     ...
;   for (int ks = 0; ks < 2; ++ks)
; #pragma unroll
;     for (int st = 0; st < 2; ++st) {
;       union { unsigned u[4]; bf16x8 v; } pf;
; #pragma unroll
;       for (int j = 0; j < 4; ++j) {
;         const int i0 = 8 * st + 2 * j;
;         f32x2v t = {S[ks][i0], S[ks][i0 + 1]};
;         t = __builtin_elementwise_fma(t, c2v, mcv);
;         f32x2v pv;
;         if (variant == 1) { pv = t; } else {
;         pv.x = __builtin_amdgcn_exp2f(t.x);
;         pv.y = __builtin_amdgcn_exp2f(t.y);
;         }
;         if (MODE != 0) {
;           if (need_mask) {
;             pv.x = (S[ks][i0] > -1e29f) ? pv.x : 0.f;
;             pv.y = (S[ks][i0 + 1] > -1e29f) ? pv.y : 0.f;
;           }
;         }
;         rs2 += pv;
;         pf.u[j] = __builtin_bit_cast(unsigned, __builtin_convertvector(pv, hwbf16x2));
;       }
; #pragma unroll
;       for (int d = 0; d < DV / 32; ++d) {
;         const char* vp = base + C::KBYTES + (d * 32 + lr) * C::VSTR + (ks * 32 + 16 * st + 4 * lh) * 2;
;         const s16x4 lo = *(const s16x4*)vp, hi = *(const s16x4*)(vp + 16);
;         const bf16x8 vf = __builtin_shufflevector(lo, hi, 0, 1, 2, 3, 4, 5, 6, 7);
;         O[d] = MFMA(vf, pf.v, O[d]);
;       }
;     }
;   float rs = rs2.x + rs2.y;
;   rs += __shfl_xor(rs, 32);
;   l += rs;
;     ...
;     if (t + NST - 1 < ntile) {
;       const int sn = (stage == 0) ? NST - 1 : stage - 1;
;       FA_ISSUE(t + NST - 1, sn)
;     }
	v_mfma_f32_32x32x16_bf16 v[80:95], v[228:231], v[130:133], v[80:95]
	v_fma_f32 v132, v112, s96, v12
	v_fma_f32 v133, v113, s96, v12
	v_fma_f32 v134, v114, s96, v12
	v_fma_f32 v135, v115, s96, v12
	v_exp_f32_e32 v132, v132
	v_exp_f32_e32 v133, v133
	v_pk_add_f32 v[130:131], v[178:179], v[176:177]
	v_cndmask_b32_e32 v112, 0, v132, vcc
	v_cmp_lt_f32_e32 vcc, s33, v113
	v_pk_add_f32 v[130:131], v[138:139], v[130:131]
	v_cndmask_b32_e64 v132, v132, v112, s[8:9]
	v_cndmask_b32_e32 v113, 0, v133, vcc
	v_cndmask_b32_e64 v133, v133, v113, s[8:9]
	v_exp_f32_e32 v113, v134
	v_exp_f32_e32 v134, v135
	v_cmp_lt_f32_e32 vcc, s33, v114
	v_cvt_pk_bf16_f32 v112, v132, v133
	v_pk_add_f32 v[130:131], v[140:141], v[130:131]
	v_cndmask_b32_e32 v114, 0, v113, vcc
	v_cmp_lt_f32_e32 vcc, s33, v115
	v_pk_add_f32 v[130:131], v[142:143], v[130:131]
	s_nop 0
	v_cndmask_b32_e32 v115, 0, v134, vcc
	v_cndmask_b32_e64 v135, v134, v115, s[8:9]
	v_cndmask_b32_e64 v134, v113, v114, s[8:9]
	v_pk_fma_f32 v[114:115], v[116:117], s[96:97], v[12:13] op_sel_hi:[1,0,0]
	v_cmp_lt_f32_e32 vcc, s33, v116
	v_exp_f32_e32 v114, v114
	v_exp_f32_e32 v115, v115
	v_cvt_pk_bf16_f32 v113, v134, v135
	v_cndmask_b32_e32 v116, 0, v114, vcc
	v_cmp_lt_f32_e32 vcc, s33, v117
	v_cndmask_b32_e64 v136, v114, v116, s[8:9]
	s_nop 0
	v_cndmask_b32_e32 v117, 0, v115, vcc
	v_cndmask_b32_e64 v137, v115, v117, s[8:9]
	v_pk_fma_f32 v[116:117], v[118:119], s[96:97], v[12:13] op_sel_hi:[1,0,0]
	v_cmp_lt_f32_e32 vcc, s33, v118
	v_exp_f32_e32 v115, v116
	v_exp_f32_e32 v116, v117
	v_cvt_pk_bf16_f32 v114, v136, v137
	v_cndmask_b32_e32 v117, 0, v115, vcc
	v_cmp_lt_f32_e32 vcc, s33, v119
	v_cndmask_b32_e64 v138, v115, v117, s[8:9]
	s_nop 0
	v_cndmask_b32_e32 v118, 0, v116, vcc
	v_cndmask_b32_e64 v139, v116, v118, s[8:9]
	s_nop 0
	v_cvt_pk_bf16_f32 v115, v138, v139
	v_cmp_lt_f32_e32 vcc, s33, v120
	s_waitcnt lgkmcnt(0)
	v_mfma_f32_32x32x16_bf16 v[96:111], v[232:235], v[112:115], v[96:111]
	s_nop 0
	s_waitcnt lgkmcnt(0)
	v_mfma_f32_32x32x16_bf16 v[80:95], v[236:239], v[112:115], v[80:95]
	v_add_f32_e64 v112, v132, v130
	v_add_f32_e64 v113, v133, v131
	v_add_f32_e64 v112, v134, v112
	v_add_f32_e64 v113, v135, v113
	v_add_f32_e64 v112, v136, v112
	v_add_f32_e64 v113, v137, v113
	v_pk_add_f32 v[130:131], v[138:139], v[112:113]
	v_pk_fma_f32 v[112:113], v[120:121], s[96:97], v[12:13] op_sel_hi:[1,0,0]
	s_nop 0
	v_exp_f32_e32 v112, v112
	v_exp_f32_e32 v113, v113
	v_cndmask_b32_e32 v114, 0, v112, vcc
	v_cmp_lt_f32_e32 vcc, s33, v121
	v_cndmask_b32_e64 v120, v112, v114, s[8:9]
	s_nop 0
	v_cndmask_b32_e32 v115, 0, v113, vcc
	v_cndmask_b32_e64 v121, v113, v115, s[8:9]
	v_pk_fma_f32 v[114:115], v[122:123], s[96:97], v[12:13] op_sel_hi:[1,0,0]
	v_cmp_lt_f32_e32 vcc, s33, v122
	v_exp_f32_e32 v113, v114
	v_exp_f32_e32 v114, v115
	v_cvt_pk_bf16_f32 v112, v120, v121
	v_cndmask_b32_e32 v115, 0, v113, vcc
	v_cmp_lt_f32_e32 vcc, s33, v123
	v_cndmask_b32_e64 v122, v113, v115, s[8:9]
	s_nop 0
	v_cndmask_b32_e32 v116, 0, v114, vcc
	v_cndmask_b32_e64 v123, v114, v116, s[8:9]
	v_pk_fma_f32 v[114:115], v[124:125], s[96:97], v[12:13] op_sel_hi:[1,0,0]
	v_cmp_lt_f32_e32 vcc, s33, v124
	v_exp_f32_e32 v114, v114
	v_exp_f32_e32 v115, v115
	v_cvt_pk_bf16_f32 v113, v122, v123
	v_cndmask_b32_e32 v116, 0, v114, vcc
	v_cmp_lt_f32_e32 vcc, s33, v125
	v_cndmask_b32_e64 v124, v114, v116, s[8:9]
	s_nop 0
	v_cndmask_b32_e32 v117, 0, v115, vcc
	v_cndmask_b32_e64 v125, v115, v117, s[8:9]
	v_pk_fma_f32 v[116:117], v[126:127], s[96:97], v[12:13] op_sel_hi:[1,0,0]
	v_cmp_lt_f32_e32 vcc, s33, v126
	v_exp_f32_e32 v12, v116
	v_exp_f32_e32 v115, v117
	v_cvt_pk_bf16_f32 v114, v124, v125
	v_cndmask_b32_e32 v116, 0, v12, vcc
	v_cmp_lt_f32_e32 vcc, s33, v127
	v_cndmask_b32_e64 v126, v12, v116, s[8:9]
	s_nop 0
	v_cndmask_b32_e32 v117, 0, v115, vcc
	v_cndmask_b32_e64 v127, v115, v117, s[8:9]
	s_nop 0
	v_cvt_pk_bf16_f32 v115, v126, v127
	s_waitcnt lgkmcnt(0)
	s_nop 0
	v_mfma_f32_32x32x16_bf16 v[96:111], v[240:243], v[112:115], v[96:111]
	s_nop 0
	s_waitcnt lgkmcnt(0)
	v_mfma_f32_32x32x16_bf16 v[80:95], v[244:247], v[112:115], v[80:95]
	v_add_f32_e64 v112, v120, v130
	v_add_f32_e64 v113, v121, v131
	v_add_f32_e64 v112, v122, v112
	v_add_f32_e64 v113, v123, v113
	v_add_f32_e64 v112, v124, v112
	v_add_f32_e64 v113, v125, v113
	v_pk_add_f32 v[112:113], v[126:127], v[112:113]
	s_nop 0
	v_add_f32_e32 v12, v112, v113
	ds_bpermute_b32 v112, v165, v12
	s_cmp_ge_i32 s21, s16
	s_cbranch_scc1 .Ldma_m_win2
	s_add_i32 s98, s0, 0xffffb800
	s_cmp_lg_u32 s22, 0
	s_cselect_b32 s98, s98, 0xd800
	v_readfirstlane_b32 s99, v15
	s_add_i32 m0, s99, s98
	v_readfirstlane_b32 s99, v13
	global_load_lds_dwordx4 v[10:11], off
	s_add_i32 m0, s99, s98
	v_readfirstlane_b32 s99, v169
	global_load_lds_dwordx4 v[8:9], off
	s_add_i32 m0, s99, s98
	s_nop 0
	global_load_lds_dwordx4 v[6:7], off

; #define MFMA(a, b, c) __builtin_amdgcn_mfma_f32_32x32x16_bf16((a), (b), (c), 0, 0, 0)
;     ...
;   for (int ks = 0; ks < 2; ++ks)
; #pragma unroll
;     for (int st = 0; st < 2; ++st) {
;       union { unsigned u[4]; bf16x8 v; } pf;
; #pragma unroll
;       for (int j = 0; j < 4; ++j) {
;         const int i0 = 8 * st + 2 * j;
;         f32x2v t = {S[ks][i0], S[ks][i0 + 1]};
;         t = __builtin_elementwise_fma(t, c2v, mcv);
;         f32x2v pv;
;         if (variant == 1) { pv = t; } else {
;         pv.x = __builtin_amdgcn_exp2f(t.x);
;         pv.y = __builtin_amdgcn_exp2f(t.y);
;         }
;         if (MODE != 0) {
;           if (need_mask) {
;             pv.x = (S[ks][i0] > -1e29f) ? pv.x : 0.f;
;             pv.y = (S[ks][i0 + 1] > -1e29f) ? pv.y : 0.f;
;           }
;         }
;         rs2 += pv;
;         pf.u[j] = __builtin_bit_cast(unsigned, __builtin_convertvector(pv, hwbf16x2));
;       }
; #pragma unroll
;       for (int d = 0; d < DV / 32; ++d) {
;         const char* vp = base + C::KBYTES + (d * 32 + lr) * C::VSTR + (ks * 32 + 16 * st + 4 * lh) * 2;
;         const s16x4 lo = *(const s16x4*)vp, hi = *(const s16x4*)(vp + 16);
;         const bf16x8 vf = __builtin_shufflevector(lo, hi, 0, 1, 2, 3, 4, 5, 6, 7);
;         O[d] = MFMA(vf, pf.v, O[d]);
;       }
;     }
;   float rs = rs2.x + rs2.y;
;   rs += __shfl_xor(rs, 32);
;   l += rs;
;     ...
;     if (t + NST - 1 < ntile) {
;       const int sn = (stage == 0) ? NST - 1 : stage - 1;
;       FA_ISSUE(t + NST - 1, sn)
;     }
.Lfast_win2:
	v_mul_f32_e32 v12, 0xbe38aa3b, v12
	v_pk_fma_f32 v[176:177], v[128:129], s[96:97], v[12:13] op_sel_hi:[1,0,0]
	v_exp_f32_e32 v184, v176
	v_exp_f32_e32 v185, v177
	v_pk_fma_f32 v[128:129], v[130:131], s[96:97], v[12:13] op_sel_hi:[1,0,0]
	v_exp_f32_e32 v186, v128
	v_exp_f32_e32 v187, v129
	v_cvt_pk_bf16_f32 v176, v184, v185
	v_pk_fma_f32 v[128:129], v[132:133], s[96:97], v[12:13] op_sel_hi:[1,0,0]
	v_exp_f32_e32 v188, v128
	v_exp_f32_e32 v189, v129
	v_cvt_pk_bf16_f32 v177, v186, v187
	v_pk_fma_f32 v[128:129], v[134:135], s[96:97], v[12:13] op_sel_hi:[1,0,0]
	v_exp_f32_e32 v134, v128
	v_exp_f32_e32 v135, v129
	v_cvt_pk_bf16_f32 v178, v188, v189
	v_cvt_pk_bf16_f32 v179, v134, v135
	s_waitcnt lgkmcnt(0)
	s_nop 0
	v_mfma_f32_32x32x16_bf16 v[96:111], v[216:219], v[176:179], v[96:111]
	s_waitcnt lgkmcnt(0)
	v_mfma_f32_32x32x16_bf16 v[80:95], v[220:223], v[176:179], v[80:95]
	v_add_f32_e64 v130, v184, 0
	v_add_f32_e64 v131, v185, 0
	v_add_f32_e64 v130, v186, v130
	v_add_f32_e64 v131, v187, v131
	v_add_f32_e64 v130, v188, v130
	v_add_f32_e64 v131, v189, v131
	v_pk_add_f32 v[176:177], v[134:135], v[130:131]
	v_pk_fma_f32 v[130:131], v[136:137], s[96:97], v[12:13] op_sel_hi:[1,0,0]
	v_exp_f32_e32 v178, v130
	v_exp_f32_e32 v179, v131
	v_pk_fma_f32 v[132:133], v[138:139], s[96:97], v[12:13] op_sel_hi:[1,0,0]
	v_exp_f32_e32 v138, v132
	v_exp_f32_e32 v139, v133
	v_cvt_pk_bf16_f32 v130, v178, v179
	v_pk_fma_f32 v[132:133], v[140:141], s[96:97], v[12:13] op_sel_hi:[1,0,0]
	v_exp_f32_e32 v140, v132
	v_exp_f32_e32 v141, v133
	v_cvt_pk_bf16_f32 v131, v138, v139
	v_pk_fma_f32 v[134:135], v[142:143], s[96:97], v[12:13] op_sel_hi:[1,0,0]
	v_exp_f32_e32 v142, v134
	v_exp_f32_e32 v143, v135
	v_cvt_pk_bf16_f32 v132, v140, v141
	v_cvt_pk_bf16_f32 v133, v142, v143
	s_nop 1
	v_mfma_f32_32x32x16_bf16 v[96:111], v[224:227], v[130:133], v[96:111]
	s_waitcnt lgkmcnt(0)
	v_mfma_f32_32x32x16_bf16 v[80:95], v[228:231], v[130:133], v[80:95]
	v_fma_f32 v132, v112, s96, v12
	v_fma_f32 v133, v113, s96, v12
	v_fma_f32 v134, v114, s96, v12
	v_fma_f32 v135, v115, s96, v12
	v_exp_f32_e32 v132, v132
	v_exp_f32_e32 v133, v133
	v_pk_add_f32 v[130:131], v[178:179], v[176:177]
	v_pk_add_f32 v[130:131], v[138:139], v[130:131]
	v_exp_f32_e32 v134, v134
	v_exp_f32_e32 v135, v135
	v_cvt_pk_bf16_f32 v112, v132, v133
	v_pk_add_f32 v[130:131], v[140:141], v[130:131]
	v_pk_add_f32 v[130:131], v[142:143], v[130:131]
	v_pk_fma_f32 v[114:115], v[116:117], s[96:97], v[12:13] op_sel_hi:[1,0,0]
	v_exp_f32_e32 v136, v114
	v_exp_f32_e32 v137, v115
	v_cvt_pk_bf16_f32 v113, v134, v135
	v_pk_fma_f32 v[116:117], v[118:119], s[96:97], v[12:13] op_sel_hi:[1,0,0]
	v_exp_f32_e32 v138, v116
	v_exp_f32_e32 v139, v117
	v_cvt_pk_bf16_f32 v114, v136, v137
	v_cvt_pk_bf16_f32 v115, v138, v139
	s_waitcnt lgkmcnt(0)
	s_nop 0
	v_mfma_f32_32x32x16_bf16 v[96:111], v[232:235], v[112:115], v[96:111]
	s_waitcnt lgkmcnt(0)
	v_mfma_f32_32x32x16_bf16 v[80:95], v[236:239], v[112:115], v[80:95]
	v_add_f32_e64 v112, v132, v130
	v_add_f32_e64 v113, v133, v131
	v_add_f32_e64 v112, v134, v112
	v_add_f32_e64 v113, v135, v113
	v_add_f32_e64 v112, v136, v112
	v_add_f32_e64 v113, v137, v113
	v_pk_add_f32 v[130:131], v[138:139], v[112:113]
	v_pk_fma_f32 v[112:113], v[120:121], s[96:97], v[12:13] op_sel_hi:[1,0,0]
	v_exp_f32_e32 v120, v112
	v_exp_f32_e32 v121, v113
	v_pk_fma_f32 v[114:115], v[122:123], s[96:97], v[12:13] op_sel_hi:[1,0,0]
	v_exp_f32_e32 v122, v114
	v_exp_f32_e32 v123, v115
	v_cvt_pk_bf16_f32 v112, v120, v121
	v_pk_fma_f32 v[114:115], v[124:125], s[96:97], v[12:13] op_sel_hi:[1,0,0]
	v_exp_f32_e32 v124, v114
	v_exp_f32_e32 v125, v115
	v_cvt_pk_bf16_f32 v113, v122, v123
	v_pk_fma_f32 v[116:117], v[126:127], s[96:97], v[12:13] op_sel_hi:[1,0,0]
	v_exp_f32_e32 v126, v116
	v_exp_f32_e32 v127, v117
	v_cvt_pk_bf16_f32 v114, v124, v125
	v_cvt_pk_bf16_f32 v115, v126, v127
	s_waitcnt lgkmcnt(0)
	s_nop 0
	v_mfma_f32_32x32x16_bf16 v[96:111], v[240:243], v[112:115], v[96:111]
	s_waitcnt lgkmcnt(0)
	v_mfma_f32_32x32x16_bf16 v[80:95], v[244:247], v[112:115], v[80:95]
	v_add_f32_e64 v112, v120, v130
	v_add_f32_e64 v113, v121, v131
	v_add_f32_e64 v112, v122, v112
	v_add_f32_e64 v113, v123, v113
	v_add_f32_e64 v112, v124, v112
	v_add_f32_e64 v113, v125, v113
	v_pk_add_f32 v[112:113], v[126:127], v[112:113]
	v_add_f32_e32 v12, v112, v113
	ds_bpermute_b32 v112, v165, v12
	s_cmp_ge_i32 s21, s16
	s_cbranch_scc1 .Ldma_f_win2
	s_add_i32 s98, s0, 0xffffb800
	s_cmp_lg_u32 s22, 0
	s_cselect_b32 s98, s98, 0xd800
	v_readfirstlane_b32 s99, v15
	s_add_i32 m0, s99, s98
	v_readfirstlane_b32 s99, v13
	global_load_lds_dwordx4 v[10:11], off
	s_add_i32 m0, s99, s98
	v_readfirstlane_b32 s99, v169
	global_load_lds_dwordx4 v[8:9], off
	s_add_i32 m0, s99, s98
	s_nop 0
	global_load_lds_dwordx4 v[6:7], off

; template <int N> DI void wait_vmcnt() { asm volatile("s_waitcnt vmcnt(%0)" ::"n"(N) : "memory"); }
;     ...
;   asm volatile("s_waitcnt vmcnt(0)" ::: "memory");
; #pragma unroll
;   for (int t = 0; t < NST - 1; ++t)
;     if (t < ntile) FA_ISSUE(t, t)
;   int stage = 0;
;   for (int t = 0; t < ntile; ++t) {
;     int ahead = ((ntile < t + NST - 1) ? ntile : t + NST - 1) - (t + 1);
;     if (NST == 4 && ahead >= 2) wait_vmcnt<2 * NI>();
;     else if (ahead >= 1) wait_vmcnt<NI>();
;     else wait_vmcnt<0>();
;     raw_barrier();
;     if (t + NST - 1 < ntile) {
;       const int sn = (stage == 0) ? NST - 1 : stage - 1;
;       FA_ISSUE(t + NST - 1, sn)
;     }
.LBB0_586:
	s_cmp_ge_i32 s21, s16
	s_cbranch_scc1 .Ldma_skip_win2
	s_add_i32 s98, s0, 0xffffb800
	s_cmp_lg_u32 s22, 0
	s_cselect_b32 s98, s98, 0xd800
	v_readfirstlane_b32 s99, v15
	s_add_i32 m0, s99, s98
	v_readfirstlane_b32 s99, v13
	global_load_lds_dwordx4 v[10:11], off
	s_add_i32 m0, s99, s98
	v_readfirstlane_b32 s99, v169
	global_load_lds_dwordx4 v[8:9], off
	s_add_i32 m0, s99, s98
	s_nop 0
	global_load_lds_dwordx4 v[6:7], off
